# out-proj K loop too: s_setprio 1 from each k-tile barrier to the 12th MFMA behind it
# speedup vs baseline: 1.0077x; 1.0077x over previous
; #define MFMA(a, b, c) __builtin_amdgcn_mfma_f32_32x32x16_bf16((a), (b), (c), 0, 0, 0)
; template <class Epi, class ColV>
; DI void gemm_tile(const bf16_t* __restrict__ A, int lda, const bf16_t* __restrict__ Bt, int ldb, int K, int m0, int n0, unsigned char* smem, Epi epi, ColV colv, const bf16_t* __restrict__ HYT = nullptr) {
;     ...
;     auto gload = [&](u32x4 (&r)[8], int kt) {
; #pragma unroll
;         for (int i = 0; i < 4; ++i) { int id = tid + 256 * i, row = id >> 3, kc = id & 7;
;             if (HYT && kt >= 12) r[i] = *(const u32x4*)(HYT + (size_t)((kt - 12) * 64 + (id >> 4)) * NT + m0 + (id & 15) * 8);
;             else r[i] = *(const u32x4*)(A + (size_t)(m0 + row) * lda + kt * 64 + kc * 8);
;             r[4 + i] = *(const u32x4*)(Bt + (size_t)(n0 + row) * ldb + kt * 64 + kc * 8); }
;     };
;     auto sstore = [&](const u32x4 (&r)[8], int buf, int kt) {
; #pragma unroll
;         for (int i = 0; i < 4; ++i) { int id = tid + 256 * i, row = id >> 3, kc = id & 7;
;             if (HYT && kt >= 12) { const int kk = id >> 4, rr = (id & 15) * 8; bf16_t* d = As + (buf * 128 + rr) * LS + kk; const bf16x8 v = __builtin_bit_cast(bf16x8, r[i]);
; #pragma unroll
;                 for (int e = 0; e < 8; ++e) d[e * LS] = (bf16_t)v[e]; }
;             else *(u32x4*)(As + (buf * 128 + row) * LS + kc * 8) = r[i];
;             *(u32x4*)(Bs + (buf * 128 + row) * LS + kc * 8) = r[4 + i]; }
;     };
;     auto step = [&](int kt, u32x4 (&ldset)[8], const u32x4 (&stset)[8]) {
;         const int buf = kt & 1;
;         if (kt + 2 < nk) gload(ldset, kt + 2);
;         const bf16_t* Ab = As + (buf * 128 + 64 * wr + li) * LS + 8 * lh;
;         const bf16_t* Bb = Bs + (buf * 128 + 64 * wc + li) * LS + 8 * lh;
;         bf16x8 fa[2][2], fb[2][2], ga[2][2], gb[2][2];
; #pragma unroll
;         for (int k2 = 0; k2 < 2; ++k2) { fa[k2][0] = ld8(Ab + 16 * k2); fa[k2][1] = ld8(Ab + 32 * LS + 16 * k2); fb[k2][0] = ld8(Bb + 16 * k2); fb[k2][1] = ld8(Bb + 32 * LS + 16 * k2); }
;         __builtin_amdgcn_sched_barrier(0);
; #pragma unroll
;         for (int k2 = 0; k2 < 2; ++k2) {
;             acc[0][0] = MFMA(fa[k2][0], fb[k2][0], acc[0][0]); acc[0][1] = MFMA(fa[k2][0], fb[k2][1], acc[0][1]);
;             acc[1][0] = MFMA(fa[k2][1], fb[k2][0], acc[1][0]); acc[1][1] = MFMA(fa[k2][1], fb[k2][1], acc[1][1]);
;         }
; #pragma unroll
.LBB0_79:
	s_ashr_i32 s12, s37, 31
	s_lshr_b32 s12, s12, 29
	s_add_i32 s12, s37, s12
	s_lshl_b32 s12, s12, 7
	s_and_b32 s38, s12, 0xfffffc00
	v_mov_b32_e32 v151, v168
	s_or_b32 s12, s38, s76
	s_ashr_i32 s13, s12, 31
	v_ashrrev_i32_e32 v38, 3, v151
	v_add_u32_e32 v0, s12, v38
	v_ashrrev_i32_e32 v1, 31, v0
	v_lshlrev_b64 v[0:1], 11, v[0:1]
	v_lshlrev_b32_e32 v2, 4, v151
	v_add_u32_e32 v40, 0x100, v151
	v_lshl_add_u64 v[0:1], s[94:95], 0, v[0:1]
	v_and_b32_e32 v2, 0x70, v2
	v_ashrrev_i32_e32 v41, 3, v40
	v_lshl_add_u64 v[160:161], v[0:1], 0, v[2:3]
	v_subrev_u32_e32 v0, s38, v38
	v_subrev_u32_e32 v16, s38, v41
	v_add_u32_e32 v42, 0x200, v151
	v_add_u32_e32 v0, s36, v0
	v_add_u32_e32 v12, s12, v41
	v_add_u32_e32 v16, s36, v16
	v_ashrrev_i32_e32 v43, 3, v42
	v_ashrrev_i32_e32 v1, 31, v0
	v_ashrrev_i32_e32 v13, 31, v12
	v_ashrrev_i32_e32 v17, 31, v16
	v_subrev_u32_e32 v24, s38, v43
	v_add_u32_e32 v44, 0x300, v151
	v_lshlrev_b64 v[0:1], 11, v[0:1]
	v_lshlrev_b64 v[12:13], 11, v[12:13]
	v_lshlrev_b64 v[16:17], 11, v[16:17]
	v_add_u32_e32 v20, s12, v43
	v_add_u32_e32 v24, s36, v24
	v_ashrrev_i32_e32 v45, 3, v44
	global_load_dwordx4 v[4:7], v[160:161], off
	v_lshl_add_u64 v[0:1], s[10:11], 0, v[0:1]
	v_lshl_add_u64 v[12:13], s[94:95], 0, v[12:13]
	v_lshl_add_u64 v[16:17], s[10:11], 0, v[16:17]
	v_ashrrev_i32_e32 v21, 31, v20
	v_ashrrev_i32_e32 v25, 31, v24
	v_subrev_u32_e32 v32, s38, v45
	v_lshl_add_u64 v[0:1], v[0:1], 0, v[2:3]
	v_lshl_add_u64 v[162:163], v[12:13], 0, v[2:3]
	v_lshl_add_u64 v[152:153], v[16:17], 0, v[2:3]
	v_lshlrev_b64 v[20:21], 11, v[20:21]
	v_lshlrev_b64 v[24:25], 11, v[24:25]
	v_add_u32_e32 v28, s12, v45
	v_add_u32_e32 v32, s36, v32
	global_load_dwordx4 v[8:11], v[0:1], off
	global_load_dwordx4 v[12:15], v[162:163], off
	global_load_dwordx4 v[16:19], v[152:153], off
	v_lshl_add_u64 v[20:21], s[94:95], 0, v[20:21]
	v_lshl_add_u64 v[24:25], s[10:11], 0, v[24:25]
	v_ashrrev_i32_e32 v29, 31, v28
	v_ashrrev_i32_e32 v33, 31, v32
	v_lshl_add_u64 v[164:165], v[20:21], 0, v[2:3]
	v_lshl_add_u64 v[154:155], v[24:25], 0, v[2:3]
	v_lshlrev_b64 v[28:29], 11, v[28:29]
	v_lshlrev_b64 v[32:33], 11, v[32:33]
	global_load_dwordx4 v[20:23], v[164:165], off
	global_load_dwordx4 v[24:27], v[154:155], off
	v_lshl_add_u64 v[28:29], s[94:95], 0, v[28:29]
	v_lshl_add_u64 v[32:33], s[10:11], 0, v[32:33]
	v_lshl_add_u64 v[166:167], v[28:29], 0, v[2:3]
	v_lshl_add_u64 v[156:157], v[32:33], 0, v[2:3]
	global_load_dwordx4 v[28:31], v[166:167], off
	global_load_dwordx4 v[32:35], v[156:157], off
	v_mul_lo_u32 v38, v38, s6
	v_add3_u32 v46, 0, v38, v2
	global_load_dwordx4 v[96:99], v[160:161], off offset:128
	global_load_dwordx4 v[92:95], v[0:1], off offset:128
	global_load_dwordx4 v[88:91], v[162:163], off offset:128
	global_load_dwordx4 v[84:87], v[152:153], off offset:128
	global_load_dwordx4 v[80:83], v[164:165], off offset:128
	global_load_dwordx4 v[76:79], v[154:155], off offset:128
	global_load_dwordx4 v[72:75], v[166:167], off offset:128
	global_load_dwordx4 v[68:71], v[156:157], off offset:128
	v_and_b32_e32 v37, 31, v151
	v_bfe_u32 v148, v151, 5, 1
	v_and_b32_e32 v36, 64, v151
	v_lshlrev_b32_e32 v39, 3, v151
	s_lshl_b64 s[40:41], s[12:13], 1
	s_add_u32 s40, s39, s40
	v_and_b32_e32 v202, 63, v151
	s_addc_u32 s41, s42, s41
	v_and_b32_e32 v205, 63, v151
	v_and_b32_e32 v204, 63, v151
	v_and_b32_e32 v203, 63, v151
	s_waitcnt vmcnt(15)
	ds_write_b128 v46, v[4:7]
	v_mul_lo_u32 v4, v41, s6
	v_add3_u32 v5, 0, v4, v2
	s_waitcnt vmcnt(14)
	ds_write_b128 v46, v[8:11] offset:36864
	s_waitcnt vmcnt(13)
	ds_write_b128 v5, v[12:15]
	s_waitcnt vmcnt(12)
	ds_write_b128 v5, v[16:19] offset:36864
	v_mul_lo_u32 v5, v43, s6
	v_add3_u32 v6, 0, v5, v2
	v_lshlrev_b32_e32 v8, 4, v148
	s_waitcnt vmcnt(11)
	ds_write_b128 v6, v[20:23]
	s_waitcnt vmcnt(10)
	ds_write_b128 v6, v[24:27] offset:36864
	v_mul_lo_u32 v6, v45, s6
	v_add3_u32 v7, 0, v6, v2
	s_waitcnt vmcnt(9)
	ds_write_b128 v7, v[28:31]
	s_waitcnt vmcnt(8)
	ds_write_b128 v7, v[32:35] offset:36864
	s_waitcnt lgkmcnt(0)
	s_barrier
	s_setprio 1
	global_load_dwordx4 v[128:131], v[160:161], off offset:256
	global_load_dwordx4 v[124:127], v[0:1], off offset:256
	global_load_dwordx4 v[120:123], v[162:163], off offset:256
	global_load_dwordx4 v[116:119], v[152:153], off offset:256
	global_load_dwordx4 v[112:115], v[164:165], off offset:256
	global_load_dwordx4 v[108:111], v[154:155], off offset:256
	global_load_dwordx4 v[104:107], v[166:167], off offset:256
	global_load_dwordx4 v[100:103], v[156:157], off offset:256
	v_ashrrev_i32_e32 v7, 1, v151
	v_and_b32_e32 v190, 0xffffffc0, v7
	v_or_b32_e32 v7, v190, v37
	v_mul_lo_u32 v7, v7, s6
	v_add3_u32 v201, 0, v7, v8
	v_and_b32_e32 v7, 0x5f, v151
	v_mul_u32_u24_e32 v7, 0x90, v7
	v_add3_u32 v200, 0, v7, v8
	v_add_u32_e32 v7, 0, v2
	v_or_b32_e32 v2, 0x80, v37
	v_add_u32_e32 v9, v2, v190
	v_or_b32_e32 v2, v2, v36
	v_mul_lo_u32 v9, v9, s6
	v_mul_u32_u24_e32 v2, 0x90, v2
	v_add3_u32 v192, 0, v9, v8
	v_add3_u32 v191, 0, v2, v8
	v_lshrrev_b32_e32 v8, 6, v151
	v_lshlrev_b32_e32 v8, 5, v8
	v_lshlrev_b32_e32 v2, 1, v8
	v_mad_u32_u24 v8, v8, s6, 0
	v_lshl_add_u64 v[158:159], s[40:41], 0, v[2:3]
	v_add_u32_e32 v198, v7, v38
	v_lshl_add_u32 v199, v202, 1, v8
	v_add_u32_e32 v196, v7, v4
	v_lshl_add_u32 v197, v205, 1, v8
	v_add_u32_e32 v194, v7, v5
	v_lshl_add_u32 v195, v204, 1, v8
	v_add_u32_e32 v2, v7, v6
	v_lshl_add_u32 v193, v203, 1, v8
	ds_read_b128 v[4:7], v201 offset:4608
	ds_read_b128 v[8:11], v200 offset:41472
	ds_read_b128 v[12:15], v201
	ds_read_b128 v[132:135], v201 offset:32
	ds_read_b128 v[136:139], v201 offset:4640
	ds_read_b128 v[16:19], v200 offset:36864
	ds_read_b128 v[140:143], v200 offset:36896
	ds_read_b128 v[144:147], v200 offset:41504
	s_waitcnt lgkmcnt(2)
; #define MFMA(a, b, c) __builtin_amdgcn_mfma_f32_32x32x16_bf16((a), (b), (c), 0, 0, 0)
; template <class Epi, class ColV>
; DI void gemm_tile(const bf16_t* __restrict__ A, int lda, const bf16_t* __restrict__ Bt, int ldb, int K, int m0, int n0, unsigned char* smem, Epi epi, ColV colv, const bf16_t* __restrict__ HYT = nullptr) {
;     ...
;     auto step = [&](int kt, u32x4 (&ldset)[8], const u32x4 (&stset)[8]) {
;         const int buf = kt & 1;
;         if (kt + 2 < nk) gload(ldset, kt + 2);
;         const bf16_t* Ab = As + (buf * 128 + 64 * wr + li) * LS + 8 * lh;
;         const bf16_t* Bb = Bs + (buf * 128 + 64 * wc + li) * LS + 8 * lh;
;         bf16x8 fa[2][2], fb[2][2], ga[2][2], gb[2][2];
; #pragma unroll
;         for (int k2 = 0; k2 < 2; ++k2) { fa[k2][0] = ld8(Ab + 16 * k2); fa[k2][1] = ld8(Ab + 32 * LS + 16 * k2); fb[k2][0] = ld8(Bb + 16 * k2); fb[k2][1] = ld8(Bb + 32 * LS + 16 * k2); }
;         __builtin_amdgcn_sched_barrier(0);
; #pragma unroll
;         for (int k2 = 0; k2 < 2; ++k2) {
;             acc[0][0] = MFMA(fa[k2][0], fb[k2][0], acc[0][0]); acc[0][1] = MFMA(fa[k2][0], fb[k2][1], acc[0][1]);
;             acc[1][0] = MFMA(fa[k2][1], fb[k2][0], acc[1][0]); acc[1][1] = MFMA(fa[k2][1], fb[k2][1], acc[1][1]);
;         }
; #pragma unroll
;         for (int k2 = 0; k2 < 2; ++k2) { const int ks = 2 + k2; ga[k2][0] = ld8(Ab + 16 * ks); ga[k2][1] = ld8(Ab + 32 * LS + 16 * ks); gb[k2][0] = ld8(Bb + 16 * ks); gb[k2][1] = ld8(Bb + 32 * LS + 16 * ks); }
; #pragma unroll
;         for (int k2 = 0; k2 < 2; ++k2) {
;             acc[0][0] = MFMA(ga[k2][0], gb[k2][0], acc[0][0]); acc[0][1] = MFMA(ga[k2][0], gb[k2][1], acc[0][1]);
;             acc[1][0] = MFMA(ga[k2][1], gb[k2][0], acc[1][0]); acc[1][1] = MFMA(ga[k2][1], gb[k2][1], acc[1][1]);
;         }
;         if (kt + 1 < nk) sstore(stset, buf ^ 1, kt + 1);
; #pragma unroll
;         for (int i = 0; i < 8; ++i) { __builtin_amdgcn_sched_group_barrier(0x008, 1, 0); __builtin_amdgcn_sched_group_barrier(0x100, 1, 0); }
; #pragma unroll
;         for (int i = 0; i < 8; ++i) { __builtin_amdgcn_sched_group_barrier(0x008, 1, 0); __builtin_amdgcn_sched_group_barrier(0x200, 1, 0); }
;         __builtin_amdgcn_sched_barrier(0);
;         __syncthreads();
	v_mfma_f32_32x32x16_bf16 v[52:67], v[12:15], v[16:19], 0
	ds_read_b128 v[174:177], v201 offset:4704
	v_mfma_f32_32x32x16_bf16 v[36:51], v[12:15], v[8:11], 0
	ds_read_b128 v[178:181], v200 offset:36928
	v_mfma_f32_32x32x16_bf16 v[20:35], v[4:7], v[16:19], 0
	ds_read_b128 v[206:209], v200 offset:36960
	v_mfma_f32_32x32x16_bf16 v[4:19], v[4:7], v[8:11], 0
	ds_read_b128 v[210:213], v200 offset:41568
	s_waitcnt lgkmcnt(5)
	v_mfma_f32_32x32x16_bf16 v[52:67], v[132:135], v[140:143], v[52:67]
	s_waitcnt lgkmcnt(4)
	v_mfma_f32_32x32x16_bf16 v[36:51], v[132:135], v[144:147], v[36:51]
	v_mfma_f32_32x32x16_bf16 v[4:19], v[136:139], v[144:147], v[4:19]
	ds_read_b128 v[144:147], v201 offset:96
	ds_read_b128 v[132:135], v201 offset:4672
	v_mfma_f32_32x32x16_bf16 v[20:35], v[136:139], v[140:143], v[20:35]
	ds_read_b128 v[140:143], v201 offset:64
	ds_read_b128 v[136:139], v200 offset:41536
	s_waitcnt lgkmcnt(1)
	v_mfma_f32_32x32x16_bf16 v[52:67], v[140:143], v[178:181], v[52:67]
	s_waitcnt vmcnt(15)
	ds_write_b128 v198, v[96:99] offset:18432
	s_waitcnt lgkmcnt(1)
	v_mfma_f32_32x32x16_bf16 v[36:51], v[140:143], v[136:139], v[36:51]
	s_waitcnt vmcnt(14)
	ds_write_b128 v198, v[92:95] offset:55296
	v_mfma_f32_32x32x16_bf16 v[20:35], v[132:135], v[178:181], v[20:35]
	s_waitcnt vmcnt(13)
	ds_write_b128 v196, v[88:91] offset:18432
	v_mfma_f32_32x32x16_bf16 v[4:19], v[132:135], v[136:139], v[4:19]
	s_setprio 0
	s_waitcnt vmcnt(12)
	ds_write_b128 v196, v[84:87] offset:55296
	v_mfma_f32_32x32x16_bf16 v[52:67], v[144:147], v[206:209], v[52:67]
	s_waitcnt vmcnt(11)
	ds_write_b128 v194, v[80:83] offset:18432
	v_mfma_f32_32x32x16_bf16 v[36:51], v[144:147], v[210:213], v[36:51]
	s_waitcnt vmcnt(10)
	ds_write_b128 v194, v[76:79] offset:55296
	v_mfma_f32_32x32x16_bf16 v[20:35], v[174:177], v[206:209], v[20:35]
	s_waitcnt vmcnt(9)
	ds_write_b128 v2, v[72:75] offset:18432
	v_mfma_f32_32x32x16_bf16 v[4:19], v[174:177], v[210:213], v[4:19]
	s_waitcnt vmcnt(8)
	ds_write_b128 v2, v[68:71] offset:55296
	s_waitcnt lgkmcnt(0)
	s_barrier
	s_setprio 1
	global_load_dwordx4 v[144:147], v[160:161], off offset:384
	global_load_dwordx4 v[140:143], v[0:1], off offset:384
	global_load_dwordx4 v[136:139], v[162:163], off offset:384
	global_load_dwordx4 v[132:135], v[152:153], off offset:384
	global_load_dwordx4 v[92:95], v[164:165], off offset:384
	global_load_dwordx4 v[84:87], v[154:155], off offset:384
	global_load_dwordx4 v[76:79], v[166:167], off offset:384
	global_load_dwordx4 v[68:71], v[156:157], off offset:384
	ds_read_b128 v[72:75], v192
	ds_read_b128 v[80:83], v192 offset:32
	ds_read_b128 v[88:91], v192 offset:4608
	ds_read_b128 v[96:99], v192 offset:4640
	ds_read_b128 v[174:177], v191 offset:36864
	ds_read_b128 v[178:181], v191 offset:36896
	ds_read_b128 v[206:209], v191 offset:41472
	ds_read_b128 v[210:213], v191 offset:41504
	s_waitcnt lgkmcnt(3)
	v_mfma_f32_32x32x16_bf16 v[52:67], v[72:75], v[174:177], v[52:67]
	s_waitcnt lgkmcnt(1)
	v_mfma_f32_32x32x16_bf16 v[36:51], v[72:75], v[206:209], v[36:51]
	v_mfma_f32_32x32x16_bf16 v[4:19], v[88:91], v[206:209], v[4:19]
	s_waitcnt lgkmcnt(0)
	v_mfma_f32_32x32x16_bf16 v[36:51], v[80:83], v[210:213], v[36:51]
	v_mfma_f32_32x32x16_bf16 v[4:19], v[96:99], v[210:213], v[4:19]
	ds_read_b128 v[210:213], v191 offset:41568
	ds_read_b128 v[72:75], v192 offset:4672
	v_mfma_f32_32x32x16_bf16 v[20:35], v[88:91], v[174:177], v[20:35]
	ds_read_b128 v[174:177], v192 offset:4704
	ds_read_b128 v[88:91], v192 offset:64
	v_mfma_f32_32x32x16_bf16 v[52:67], v[80:83], v[178:181], v[52:67]
	ds_read_b128 v[206:209], v191 offset:36960
	ds_read_b128 v[80:83], v191 offset:41536
	v_mfma_f32_32x32x16_bf16 v[20:35], v[96:99], v[178:181], v[20:35]
	ds_read_b128 v[178:181], v191 offset:36928
	ds_read_b128 v[96:99], v192 offset:96
	s_waitcnt lgkmcnt(1)
	v_mfma_f32_32x32x16_bf16 v[52:67], v[88:91], v[178:181], v[52:67]
	s_waitcnt vmcnt(15)
	ds_write_b128 v198, v[128:131]
	v_mfma_f32_32x32x16_bf16 v[36:51], v[88:91], v[80:83], v[36:51]
	s_waitcnt vmcnt(14)
	ds_write_b128 v198, v[124:127] offset:36864
	v_mfma_f32_32x32x16_bf16 v[20:35], v[72:75], v[178:181], v[20:35]
	s_waitcnt vmcnt(13)
	ds_write_b128 v196, v[120:123]
	v_mfma_f32_32x32x16_bf16 v[4:19], v[72:75], v[80:83], v[4:19]
	s_setprio 0
	s_waitcnt vmcnt(12)
	ds_write_b128 v196, v[116:119] offset:36864
	s_waitcnt lgkmcnt(4)
	v_mfma_f32_32x32x16_bf16 v[52:67], v[96:99], v[206:209], v[52:67]
	s_waitcnt vmcnt(11)
	ds_write_b128 v194, v[112:115]
	v_mfma_f32_32x32x16_bf16 v[36:51], v[96:99], v[210:213], v[36:51]
	s_waitcnt vmcnt(10)
	ds_write_b128 v194, v[108:111] offset:36864
	v_mfma_f32_32x32x16_bf16 v[20:35], v[174:177], v[206:209], v[20:35]
	s_waitcnt vmcnt(9)
	ds_write_b128 v2, v[104:107]
	v_mfma_f32_32x32x16_bf16 v[4:19], v[174:177], v[210:213], v[4:19]
	s_waitcnt vmcnt(8)
	ds_write_b128 v2, v[100:103] offset:36864
	s_waitcnt lgkmcnt(0)
	s_barrier
; #define MFMA(a, b, c) __builtin_amdgcn_mfma_f32_32x32x16_bf16((a), (b), (c), 0, 0, 0)
; template <class Epi, class ColV>
; DI void gemm_tile(const bf16_t* __restrict__ A, int lda, const bf16_t* __restrict__ Bt, int ldb, int K, int m0, int n0, unsigned char* smem, Epi epi, ColV colv, const bf16_t* __restrict__ HYT = nullptr) {
;     ...
;     auto step = [&](int kt, u32x4 (&ldset)[8], const u32x4 (&stset)[8]) {
;         const int buf = kt & 1;
;         if (kt + 2 < nk) gload(ldset, kt + 2);
;         const bf16_t* Ab = As + (buf * 128 + 64 * wr + li) * LS + 8 * lh;
;         const bf16_t* Bb = Bs + (buf * 128 + 64 * wc + li) * LS + 8 * lh;
;         bf16x8 fa[2][2], fb[2][2], ga[2][2], gb[2][2];
; #pragma unroll
;         for (int k2 = 0; k2 < 2; ++k2) { fa[k2][0] = ld8(Ab + 16 * k2); fa[k2][1] = ld8(Ab + 32 * LS + 16 * k2); fb[k2][0] = ld8(Bb + 16 * k2); fb[k2][1] = ld8(Bb + 32 * LS + 16 * k2); }
;         __builtin_amdgcn_sched_barrier(0);
; #pragma unroll
;         for (int k2 = 0; k2 < 2; ++k2) {
;             acc[0][0] = MFMA(fa[k2][0], fb[k2][0], acc[0][0]); acc[0][1] = MFMA(fa[k2][0], fb[k2][1], acc[0][1]);
;             acc[1][0] = MFMA(fa[k2][1], fb[k2][0], acc[1][0]); acc[1][1] = MFMA(fa[k2][1], fb[k2][1], acc[1][1]);
;         }
; #pragma unroll
;         for (int k2 = 0; k2 < 2; ++k2) { const int ks = 2 + k2; ga[k2][0] = ld8(Ab + 16 * ks); ga[k2][1] = ld8(Ab + 32 * LS + 16 * ks); gb[k2][0] = ld8(Bb + 16 * ks); gb[k2][1] = ld8(Bb + 32 * LS + 16 * ks); }
; #pragma unroll
;         for (int k2 = 0; k2 < 2; ++k2) {
;             acc[0][0] = MFMA(ga[k2][0], gb[k2][0], acc[0][0]); acc[0][1] = MFMA(ga[k2][0], gb[k2][1], acc[0][1]);
;             acc[1][0] = MFMA(ga[k2][1], gb[k2][0], acc[1][0]); acc[1][1] = MFMA(ga[k2][1], gb[k2][1], acc[1][1]);
;         }
;         if (kt + 1 < nk) sstore(stset, buf ^ 1, kt + 1);
; #pragma unroll
;         for (int i = 0; i < 8; ++i) { __builtin_amdgcn_sched_group_barrier(0x008, 1, 0); __builtin_amdgcn_sched_group_barrier(0x100, 1, 0); }
; #pragma unroll
;         for (int i = 0; i < 8; ++i) { __builtin_amdgcn_sched_group_barrier(0x008, 1, 0); __builtin_amdgcn_sched_group_barrier(0x200, 1, 0); }
;         __builtin_amdgcn_sched_barrier(0);
;         __syncthreads();
	s_setprio 1
	global_load_dwordx4 v[124:127], v[160:161], off offset:512
	global_load_dwordx4 v[116:119], v[0:1], off offset:512
	global_load_dwordx4 v[108:111], v[162:163], off offset:512
	global_load_dwordx4 v[100:103], v[152:153], off offset:512
	global_load_dwordx4 v[96:99], v[164:165], off offset:512
	global_load_dwordx4 v[88:91], v[154:155], off offset:512
	global_load_dwordx4 v[80:83], v[166:167], off offset:512
	global_load_dwordx4 v[72:75], v[156:157], off offset:512
	ds_read_b128 v[104:107], v201
	ds_read_b128 v[112:115], v201 offset:32
	ds_read_b128 v[120:123], v201 offset:4608
	ds_read_b128 v[128:131], v201 offset:4640
	ds_read_b128 v[174:177], v200 offset:36864
	ds_read_b128 v[178:181], v200 offset:36896
	ds_read_b128 v[206:209], v200 offset:41472
	ds_read_b128 v[210:213], v200 offset:41504
	s_waitcnt lgkmcnt(3)
	v_mfma_f32_32x32x16_bf16 v[52:67], v[104:107], v[174:177], v[52:67]
	s_waitcnt lgkmcnt(1)
	v_mfma_f32_32x32x16_bf16 v[36:51], v[104:107], v[206:209], v[36:51]
	v_mfma_f32_32x32x16_bf16 v[4:19], v[120:123], v[206:209], v[4:19]
	s_waitcnt lgkmcnt(0)
	v_mfma_f32_32x32x16_bf16 v[36:51], v[112:115], v[210:213], v[36:51]
	v_mfma_f32_32x32x16_bf16 v[4:19], v[128:131], v[210:213], v[4:19]
	ds_read_b128 v[210:213], v200 offset:41568
	ds_read_b128 v[104:107], v201 offset:4672
	v_mfma_f32_32x32x16_bf16 v[20:35], v[120:123], v[174:177], v[20:35]
	ds_read_b128 v[174:177], v201 offset:4704
	ds_read_b128 v[120:123], v201 offset:64
	v_mfma_f32_32x32x16_bf16 v[52:67], v[112:115], v[178:181], v[52:67]
	ds_read_b128 v[206:209], v200 offset:36960
	ds_read_b128 v[112:115], v200 offset:41536
	v_mfma_f32_32x32x16_bf16 v[20:35], v[128:131], v[178:181], v[20:35]
	ds_read_b128 v[178:181], v200 offset:36928
	ds_read_b128 v[128:131], v201 offset:96
	s_waitcnt lgkmcnt(1)
	v_mfma_f32_32x32x16_bf16 v[52:67], v[120:123], v[178:181], v[52:67]
	s_waitcnt vmcnt(15)
	ds_write_b128 v198, v[144:147] offset:18432
	v_mfma_f32_32x32x16_bf16 v[36:51], v[120:123], v[112:115], v[36:51]
	s_waitcnt vmcnt(14)
	ds_write_b128 v198, v[140:143] offset:55296
	v_mfma_f32_32x32x16_bf16 v[20:35], v[104:107], v[178:181], v[20:35]
	s_waitcnt vmcnt(13)
	ds_write_b128 v196, v[136:139] offset:18432
	v_mfma_f32_32x32x16_bf16 v[4:19], v[104:107], v[112:115], v[4:19]
	s_setprio 0
	s_waitcnt vmcnt(12)
	ds_write_b128 v196, v[132:135] offset:55296
	s_waitcnt lgkmcnt(4)
	v_mfma_f32_32x32x16_bf16 v[52:67], v[128:131], v[206:209], v[52:67]
	s_waitcnt vmcnt(11)
	ds_write_b128 v194, v[92:95] offset:18432
	v_mfma_f32_32x32x16_bf16 v[36:51], v[128:131], v[210:213], v[36:51]
	s_waitcnt vmcnt(10)
	ds_write_b128 v194, v[84:87] offset:55296
	v_mfma_f32_32x32x16_bf16 v[20:35], v[174:177], v[206:209], v[20:35]
	s_waitcnt vmcnt(9)
	ds_write_b128 v2, v[76:79] offset:18432
	v_mfma_f32_32x32x16_bf16 v[4:19], v[174:177], v[210:213], v[4:19]
	s_waitcnt vmcnt(8)
	ds_write_b128 v2, v[68:71] offset:55296
	s_waitcnt lgkmcnt(0)
	s_barrier
	s_setprio 1
	global_load_dwordx4 v[128:131], v[160:161], off offset:640
	global_load_dwordx4 v[120:123], v[0:1], off offset:640
	global_load_dwordx4 v[112:115], v[162:163], off offset:640
	global_load_dwordx4 v[104:107], v[152:153], off offset:640
	global_load_dwordx4 v[92:95], v[164:165], off offset:640
	global_load_dwordx4 v[84:87], v[154:155], off offset:640
	global_load_dwordx4 v[76:79], v[166:167], off offset:640
	global_load_dwordx4 v[68:71], v[156:157], off offset:640
	ds_read_b128 v[132:135], v192
	ds_read_b128 v[136:139], v192 offset:32
	ds_read_b128 v[140:143], v192 offset:4608
	ds_read_b128 v[144:147], v192 offset:4640
	ds_read_b128 v[174:177], v191 offset:36864
	ds_read_b128 v[178:181], v191 offset:36896
	ds_read_b128 v[206:209], v191 offset:41472
	ds_read_b128 v[210:213], v191 offset:41504
	s_waitcnt lgkmcnt(3)
	v_mfma_f32_32x32x16_bf16 v[52:67], v[132:135], v[174:177], v[52:67]
	s_waitcnt lgkmcnt(1)
	v_mfma_f32_32x32x16_bf16 v[36:51], v[132:135], v[206:209], v[36:51]
	v_mfma_f32_32x32x16_bf16 v[4:19], v[140:143], v[206:209], v[4:19]
	s_waitcnt lgkmcnt(0)
	v_mfma_f32_32x32x16_bf16 v[36:51], v[136:139], v[210:213], v[36:51]
	v_mfma_f32_32x32x16_bf16 v[4:19], v[144:147], v[210:213], v[4:19]
	ds_read_b128 v[210:213], v191 offset:41568
	ds_read_b128 v[132:135], v192 offset:4672
	v_mfma_f32_32x32x16_bf16 v[20:35], v[140:143], v[174:177], v[20:35]
	ds_read_b128 v[174:177], v192 offset:4704
	ds_read_b128 v[140:143], v192 offset:64
	v_mfma_f32_32x32x16_bf16 v[52:67], v[136:139], v[178:181], v[52:67]
	ds_read_b128 v[206:209], v191 offset:36960
	ds_read_b128 v[136:139], v191 offset:41536
	v_mfma_f32_32x32x16_bf16 v[20:35], v[144:147], v[178:181], v[20:35]
	ds_read_b128 v[178:181], v191 offset:36928
	ds_read_b128 v[144:147], v192 offset:96
	s_waitcnt lgkmcnt(1)
	v_mfma_f32_32x32x16_bf16 v[52:67], v[140:143], v[178:181], v[52:67]
	s_waitcnt vmcnt(15)
	ds_write_b128 v198, v[124:127]
	v_mfma_f32_32x32x16_bf16 v[36:51], v[140:143], v[136:139], v[36:51]
	s_waitcnt vmcnt(14)
	ds_write_b128 v198, v[116:119] offset:36864
	v_mfma_f32_32x32x16_bf16 v[20:35], v[132:135], v[178:181], v[20:35]
	s_waitcnt vmcnt(13)
	ds_write_b128 v196, v[108:111]
	v_mfma_f32_32x32x16_bf16 v[4:19], v[132:135], v[136:139], v[4:19]
	s_setprio 0
	s_waitcnt vmcnt(12)
	ds_write_b128 v196, v[100:103] offset:36864
	s_waitcnt lgkmcnt(4)
	v_mfma_f32_32x32x16_bf16 v[52:67], v[144:147], v[206:209], v[52:67]
	s_waitcnt vmcnt(11)
	ds_write_b128 v194, v[96:99]
	v_mfma_f32_32x32x16_bf16 v[36:51], v[144:147], v[210:213], v[36:51]
	s_waitcnt vmcnt(10)
	ds_write_b128 v194, v[88:91] offset:36864
	v_mfma_f32_32x32x16_bf16 v[20:35], v[174:177], v[206:209], v[20:35]
	s_waitcnt vmcnt(9)
	ds_write_b128 v2, v[80:83]
	v_mfma_f32_32x32x16_bf16 v[4:19], v[174:177], v[210:213], v[4:19]
	s_waitcnt vmcnt(8)
	ds_write_b128 v2, v[72:75] offset:36864
	s_waitcnt lgkmcnt(0)
	s_barrier
; #define MFMA(a, b, c) __builtin_amdgcn_mfma_f32_32x32x16_bf16((a), (b), (c), 0, 0, 0)
; template <class Epi, class ColV>
; DI void gemm_tile(const bf16_t* __restrict__ A, int lda, const bf16_t* __restrict__ Bt, int ldb, int K, int m0, int n0, unsigned char* smem, Epi epi, ColV colv, const bf16_t* __restrict__ HYT = nullptr) {
;     ...
;     auto step = [&](int kt, u32x4 (&ldset)[8], const u32x4 (&stset)[8]) {
;         const int buf = kt & 1;
;         if (kt + 2 < nk) gload(ldset, kt + 2);
;         const bf16_t* Ab = As + (buf * 128 + 64 * wr + li) * LS + 8 * lh;
;         const bf16_t* Bb = Bs + (buf * 128 + 64 * wc + li) * LS + 8 * lh;
;         bf16x8 fa[2][2], fb[2][2], ga[2][2], gb[2][2];
; #pragma unroll
;         for (int k2 = 0; k2 < 2; ++k2) { fa[k2][0] = ld8(Ab + 16 * k2); fa[k2][1] = ld8(Ab + 32 * LS + 16 * k2); fb[k2][0] = ld8(Bb + 16 * k2); fb[k2][1] = ld8(Bb + 32 * LS + 16 * k2); }
;         __builtin_amdgcn_sched_barrier(0);
; #pragma unroll
;         for (int k2 = 0; k2 < 2; ++k2) {
;             acc[0][0] = MFMA(fa[k2][0], fb[k2][0], acc[0][0]); acc[0][1] = MFMA(fa[k2][0], fb[k2][1], acc[0][1]);
;             acc[1][0] = MFMA(fa[k2][1], fb[k2][0], acc[1][0]); acc[1][1] = MFMA(fa[k2][1], fb[k2][1], acc[1][1]);
;         }
; #pragma unroll
;         for (int k2 = 0; k2 < 2; ++k2) { const int ks = 2 + k2; ga[k2][0] = ld8(Ab + 16 * ks); ga[k2][1] = ld8(Ab + 32 * LS + 16 * ks); gb[k2][0] = ld8(Bb + 16 * ks); gb[k2][1] = ld8(Bb + 32 * LS + 16 * ks); }
; #pragma unroll
;         for (int k2 = 0; k2 < 2; ++k2) {
;             acc[0][0] = MFMA(ga[k2][0], gb[k2][0], acc[0][0]); acc[0][1] = MFMA(ga[k2][0], gb[k2][1], acc[0][1]);
;             acc[1][0] = MFMA(ga[k2][1], gb[k2][0], acc[1][0]); acc[1][1] = MFMA(ga[k2][1], gb[k2][1], acc[1][1]);
;         }
;         if (kt + 1 < nk) sstore(stset, buf ^ 1, kt + 1);
; #pragma unroll
;         for (int i = 0; i < 8; ++i) { __builtin_amdgcn_sched_group_barrier(0x008, 1, 0); __builtin_amdgcn_sched_group_barrier(0x100, 1, 0); }
; #pragma unroll
;         for (int i = 0; i < 8; ++i) { __builtin_amdgcn_sched_group_barrier(0x008, 1, 0); __builtin_amdgcn_sched_group_barrier(0x200, 1, 0); }
;         __builtin_amdgcn_sched_barrier(0);
;         __syncthreads();
	s_setprio 1
	global_load_dwordx4 v[124:127], v[160:161], off offset:768
	global_load_dwordx4 v[116:119], v[0:1], off offset:768
	global_load_dwordx4 v[108:111], v[162:163], off offset:768
	global_load_dwordx4 v[100:103], v[152:153], off offset:768
	global_load_dwordx4 v[96:99], v[164:165], off offset:768
	global_load_dwordx4 v[88:91], v[154:155], off offset:768
	global_load_dwordx4 v[80:83], v[166:167], off offset:768
	global_load_dwordx4 v[72:75], v[156:157], off offset:768
	ds_read_b128 v[132:135], v201
	ds_read_b128 v[136:139], v201 offset:32
	ds_read_b128 v[140:143], v201 offset:4608
	ds_read_b128 v[144:147], v201 offset:4640
	ds_read_b128 v[174:177], v200 offset:36864
	ds_read_b128 v[178:181], v200 offset:36896
	ds_read_b128 v[206:209], v200 offset:41472
	ds_read_b128 v[210:213], v200 offset:41504
	s_waitcnt lgkmcnt(3)
	v_mfma_f32_32x32x16_bf16 v[52:67], v[132:135], v[174:177], v[52:67]
	s_waitcnt lgkmcnt(1)
	v_mfma_f32_32x32x16_bf16 v[36:51], v[132:135], v[206:209], v[36:51]
	v_mfma_f32_32x32x16_bf16 v[4:19], v[140:143], v[206:209], v[4:19]
	s_waitcnt lgkmcnt(0)
	v_mfma_f32_32x32x16_bf16 v[36:51], v[136:139], v[210:213], v[36:51]
	v_mfma_f32_32x32x16_bf16 v[4:19], v[144:147], v[210:213], v[4:19]
	ds_read_b128 v[210:213], v200 offset:41568
	ds_read_b128 v[132:135], v201 offset:4672
	v_mfma_f32_32x32x16_bf16 v[20:35], v[140:143], v[174:177], v[20:35]
	ds_read_b128 v[174:177], v201 offset:4704
	ds_read_b128 v[140:143], v201 offset:64
	v_mfma_f32_32x32x16_bf16 v[52:67], v[136:139], v[178:181], v[52:67]
	ds_read_b128 v[206:209], v200 offset:36960
	ds_read_b128 v[136:139], v200 offset:41536
	v_mfma_f32_32x32x16_bf16 v[20:35], v[144:147], v[178:181], v[20:35]
	ds_read_b128 v[178:181], v200 offset:36928
	ds_read_b128 v[144:147], v201 offset:96
	s_waitcnt lgkmcnt(1)
	v_mfma_f32_32x32x16_bf16 v[52:67], v[140:143], v[178:181], v[52:67]
	s_waitcnt vmcnt(15)
	ds_write_b128 v198, v[128:131] offset:18432
	v_mfma_f32_32x32x16_bf16 v[36:51], v[140:143], v[136:139], v[36:51]
	s_waitcnt vmcnt(14)
	ds_write_b128 v198, v[120:123] offset:55296
	v_mfma_f32_32x32x16_bf16 v[20:35], v[132:135], v[178:181], v[20:35]
	s_waitcnt vmcnt(13)
	ds_write_b128 v196, v[112:115] offset:18432
	v_mfma_f32_32x32x16_bf16 v[4:19], v[132:135], v[136:139], v[4:19]
	s_setprio 0
	s_waitcnt vmcnt(12)
	ds_write_b128 v196, v[104:107] offset:55296
	s_waitcnt lgkmcnt(4)
	v_mfma_f32_32x32x16_bf16 v[52:67], v[144:147], v[206:209], v[52:67]
	s_waitcnt vmcnt(11)
	ds_write_b128 v194, v[92:95] offset:18432
	v_mfma_f32_32x32x16_bf16 v[36:51], v[144:147], v[210:213], v[36:51]
	s_waitcnt vmcnt(10)
	ds_write_b128 v194, v[84:87] offset:55296
	v_mfma_f32_32x32x16_bf16 v[20:35], v[174:177], v[206:209], v[20:35]
	s_waitcnt vmcnt(9)
	ds_write_b128 v2, v[76:79] offset:18432
	v_mfma_f32_32x32x16_bf16 v[4:19], v[174:177], v[210:213], v[4:19]
	s_waitcnt vmcnt(8)
	ds_write_b128 v2, v[68:71] offset:55296
	s_waitcnt lgkmcnt(0)
	s_barrier
	s_setprio 1
	global_load_dwordx4 v[128:131], v[160:161], off offset:896
	global_load_dwordx4 v[120:123], v[0:1], off offset:896
	global_load_dwordx4 v[112:115], v[162:163], off offset:896
	global_load_dwordx4 v[104:107], v[152:153], off offset:896
	global_load_dwordx4 v[92:95], v[164:165], off offset:896
	global_load_dwordx4 v[84:87], v[154:155], off offset:896
	global_load_dwordx4 v[76:79], v[166:167], off offset:896
	global_load_dwordx4 v[68:71], v[156:157], off offset:896
	ds_read_b128 v[132:135], v192
	ds_read_b128 v[136:139], v192 offset:32
	ds_read_b128 v[140:143], v192 offset:4608
	ds_read_b128 v[144:147], v192 offset:4640
	ds_read_b128 v[174:177], v191 offset:36864
	ds_read_b128 v[178:181], v191 offset:36896
	ds_read_b128 v[206:209], v191 offset:41472
	ds_read_b128 v[210:213], v191 offset:41504
	s_waitcnt lgkmcnt(3)
	v_mfma_f32_32x32x16_bf16 v[52:67], v[132:135], v[174:177], v[52:67]
	s_waitcnt lgkmcnt(1)
	v_mfma_f32_32x32x16_bf16 v[36:51], v[132:135], v[206:209], v[36:51]
	v_mfma_f32_32x32x16_bf16 v[4:19], v[140:143], v[206:209], v[4:19]
	s_waitcnt lgkmcnt(0)
	v_mfma_f32_32x32x16_bf16 v[36:51], v[136:139], v[210:213], v[36:51]
	v_mfma_f32_32x32x16_bf16 v[4:19], v[144:147], v[210:213], v[4:19]
	ds_read_b128 v[210:213], v191 offset:41568
	ds_read_b128 v[132:135], v192 offset:4672
	v_mfma_f32_32x32x16_bf16 v[20:35], v[140:143], v[174:177], v[20:35]
	ds_read_b128 v[174:177], v192 offset:4704
	ds_read_b128 v[140:143], v192 offset:64
	v_mfma_f32_32x32x16_bf16 v[52:67], v[136:139], v[178:181], v[52:67]
	ds_read_b128 v[206:209], v191 offset:36960
	ds_read_b128 v[136:139], v191 offset:41536
	v_mfma_f32_32x32x16_bf16 v[20:35], v[144:147], v[178:181], v[20:35]
	ds_read_b128 v[178:181], v191 offset:36928
	ds_read_b128 v[144:147], v192 offset:96
	s_waitcnt lgkmcnt(1)
	v_mfma_f32_32x32x16_bf16 v[52:67], v[140:143], v[178:181], v[52:67]
	s_waitcnt vmcnt(15)
	ds_write_b128 v198, v[124:127]
	v_mfma_f32_32x32x16_bf16 v[36:51], v[140:143], v[136:139], v[36:51]
	s_waitcnt vmcnt(14)
	ds_write_b128 v198, v[116:119] offset:36864
	v_mfma_f32_32x32x16_bf16 v[20:35], v[132:135], v[178:181], v[20:35]
	s_waitcnt vmcnt(13)
	ds_write_b128 v196, v[108:111]
	v_mfma_f32_32x32x16_bf16 v[4:19], v[132:135], v[136:139], v[4:19]
	s_setprio 0
	s_waitcnt vmcnt(12)
	ds_write_b128 v196, v[100:103] offset:36864
	s_waitcnt lgkmcnt(4)
	v_mfma_f32_32x32x16_bf16 v[52:67], v[144:147], v[206:209], v[52:67]
	s_waitcnt vmcnt(11)
	ds_write_b128 v194, v[96:99]
	v_mfma_f32_32x32x16_bf16 v[36:51], v[144:147], v[210:213], v[36:51]
	s_waitcnt vmcnt(10)
	ds_write_b128 v194, v[88:91] offset:36864
	v_mfma_f32_32x32x16_bf16 v[20:35], v[174:177], v[206:209], v[20:35]
	s_waitcnt vmcnt(9)
	ds_write_b128 v2, v[80:83]
	v_mfma_f32_32x32x16_bf16 v[4:19], v[174:177], v[210:213], v[4:19]
	s_waitcnt vmcnt(8)
	ds_write_b128 v2, v[72:75] offset:36864
	s_waitcnt lgkmcnt(0)
	s_barrier
; #define MFMA(a, b, c) __builtin_amdgcn_mfma_f32_32x32x16_bf16((a), (b), (c), 0, 0, 0)
; template <class Epi, class ColV>
; DI void gemm_tile(const bf16_t* __restrict__ A, int lda, const bf16_t* __restrict__ Bt, int ldb, int K, int m0, int n0, unsigned char* smem, Epi epi, ColV colv, const bf16_t* __restrict__ HYT = nullptr) {
;     ...
;     auto step = [&](int kt, u32x4 (&ldset)[8], const u32x4 (&stset)[8]) {
;         const int buf = kt & 1;
;         if (kt + 2 < nk) gload(ldset, kt + 2);
;         const bf16_t* Ab = As + (buf * 128 + 64 * wr + li) * LS + 8 * lh;
;         const bf16_t* Bb = Bs + (buf * 128 + 64 * wc + li) * LS + 8 * lh;
;         bf16x8 fa[2][2], fb[2][2], ga[2][2], gb[2][2];
; #pragma unroll
;         for (int k2 = 0; k2 < 2; ++k2) { fa[k2][0] = ld8(Ab + 16 * k2); fa[k2][1] = ld8(Ab + 32 * LS + 16 * k2); fb[k2][0] = ld8(Bb + 16 * k2); fb[k2][1] = ld8(Bb + 32 * LS + 16 * k2); }
;         __builtin_amdgcn_sched_barrier(0);
; #pragma unroll
;         for (int k2 = 0; k2 < 2; ++k2) {
;             acc[0][0] = MFMA(fa[k2][0], fb[k2][0], acc[0][0]); acc[0][1] = MFMA(fa[k2][0], fb[k2][1], acc[0][1]);
;             acc[1][0] = MFMA(fa[k2][1], fb[k2][0], acc[1][0]); acc[1][1] = MFMA(fa[k2][1], fb[k2][1], acc[1][1]);
;         }
; #pragma unroll
;         for (int k2 = 0; k2 < 2; ++k2) { const int ks = 2 + k2; ga[k2][0] = ld8(Ab + 16 * ks); ga[k2][1] = ld8(Ab + 32 * LS + 16 * ks); gb[k2][0] = ld8(Bb + 16 * ks); gb[k2][1] = ld8(Bb + 32 * LS + 16 * ks); }
; #pragma unroll
;         for (int k2 = 0; k2 < 2; ++k2) {
;             acc[0][0] = MFMA(ga[k2][0], gb[k2][0], acc[0][0]); acc[0][1] = MFMA(ga[k2][0], gb[k2][1], acc[0][1]);
;             acc[1][0] = MFMA(ga[k2][1], gb[k2][0], acc[1][0]); acc[1][1] = MFMA(ga[k2][1], gb[k2][1], acc[1][1]);
;         }
;         if (kt + 1 < nk) sstore(stset, buf ^ 1, kt + 1);
; #pragma unroll
;         for (int i = 0; i < 8; ++i) { __builtin_amdgcn_sched_group_barrier(0x008, 1, 0); __builtin_amdgcn_sched_group_barrier(0x100, 1, 0); }
; #pragma unroll
;         for (int i = 0; i < 8; ++i) { __builtin_amdgcn_sched_group_barrier(0x008, 1, 0); __builtin_amdgcn_sched_group_barrier(0x200, 1, 0); }
;         __builtin_amdgcn_sched_barrier(0);
;         __syncthreads();
	s_setprio 1
	global_load_dwordx4 v[132:135], v[160:161], off offset:1024
	global_load_dwordx4 v[124:127], v[0:1], off offset:1024
	global_load_dwordx4 v[108:111], v[162:163], off offset:1024
	global_load_dwordx4 v[100:103], v[152:153], off offset:1024
	global_load_dwordx4 v[96:99], v[164:165], off offset:1024
	global_load_dwordx4 v[88:91], v[154:155], off offset:1024
	global_load_dwordx4 v[80:83], v[166:167], off offset:1024
	global_load_dwordx4 v[72:75], v[156:157], off offset:1024
	ds_read_b128 v[116:119], v201
	ds_read_b128 v[136:139], v201 offset:32
	ds_read_b128 v[140:143], v201 offset:4608
	ds_read_b128 v[144:147], v201 offset:4640
	ds_read_b128 v[174:177], v200 offset:36864
	ds_read_b128 v[178:181], v200 offset:36896
	ds_read_b128 v[206:209], v200 offset:41472
	ds_read_b128 v[210:213], v200 offset:41504
	s_waitcnt lgkmcnt(3)
	v_mfma_f32_32x32x16_bf16 v[52:67], v[116:119], v[174:177], v[52:67]
	s_waitcnt lgkmcnt(1)
	v_mfma_f32_32x32x16_bf16 v[36:51], v[116:119], v[206:209], v[36:51]
	v_mfma_f32_32x32x16_bf16 v[4:19], v[140:143], v[206:209], v[4:19]
	s_waitcnt lgkmcnt(0)
	v_mfma_f32_32x32x16_bf16 v[36:51], v[136:139], v[210:213], v[36:51]
	v_mfma_f32_32x32x16_bf16 v[4:19], v[144:147], v[210:213], v[4:19]
	ds_read_b128 v[210:213], v200 offset:41568
	ds_read_b128 v[116:119], v201 offset:4672
	v_mfma_f32_32x32x16_bf16 v[20:35], v[140:143], v[174:177], v[20:35]
	ds_read_b128 v[174:177], v201 offset:4704
	ds_read_b128 v[140:143], v201 offset:64
	v_mfma_f32_32x32x16_bf16 v[52:67], v[136:139], v[178:181], v[52:67]
	ds_read_b128 v[206:209], v200 offset:36960
	ds_read_b128 v[136:139], v200 offset:41536
	v_mfma_f32_32x32x16_bf16 v[20:35], v[144:147], v[178:181], v[20:35]
	ds_read_b128 v[178:181], v200 offset:36928
	ds_read_b128 v[144:147], v201 offset:96
	s_waitcnt lgkmcnt(1)
	v_mfma_f32_32x32x16_bf16 v[52:67], v[140:143], v[178:181], v[52:67]
	s_waitcnt vmcnt(15)
	ds_write_b128 v198, v[128:131] offset:18432
	v_mfma_f32_32x32x16_bf16 v[36:51], v[140:143], v[136:139], v[36:51]
	s_waitcnt vmcnt(14)
	ds_write_b128 v198, v[120:123] offset:55296
	v_mfma_f32_32x32x16_bf16 v[20:35], v[116:119], v[178:181], v[20:35]
	s_waitcnt vmcnt(13)
	ds_write_b128 v196, v[112:115] offset:18432
	v_mfma_f32_32x32x16_bf16 v[4:19], v[116:119], v[136:139], v[4:19]
	s_setprio 0
	s_waitcnt vmcnt(12)
	ds_write_b128 v196, v[104:107] offset:55296
	s_waitcnt lgkmcnt(4)
	v_mfma_f32_32x32x16_bf16 v[52:67], v[144:147], v[206:209], v[52:67]
	s_waitcnt vmcnt(11)
	ds_write_b128 v194, v[92:95] offset:18432
	v_mfma_f32_32x32x16_bf16 v[36:51], v[144:147], v[210:213], v[36:51]
	s_waitcnt vmcnt(10)
	ds_write_b128 v194, v[84:87] offset:55296
	v_mfma_f32_32x32x16_bf16 v[20:35], v[174:177], v[206:209], v[20:35]
	s_waitcnt vmcnt(9)
	ds_write_b128 v2, v[76:79] offset:18432
	v_mfma_f32_32x32x16_bf16 v[4:19], v[174:177], v[210:213], v[4:19]
	s_waitcnt vmcnt(8)
	ds_write_b128 v2, v[68:71] offset:55296
	s_waitcnt lgkmcnt(0)
	s_barrier
	s_setprio 1
	global_load_dwordx4 v[136:139], v[160:161], off offset:1152
	global_load_dwordx4 v[128:131], v[0:1], off offset:1152
	global_load_dwordx4 v[116:119], v[162:163], off offset:1152
	global_load_dwordx4 v[104:107], v[152:153], off offset:1152
	global_load_dwordx4 v[92:95], v[164:165], off offset:1152
	global_load_dwordx4 v[84:87], v[154:155], off offset:1152
	global_load_dwordx4 v[76:79], v[166:167], off offset:1152
	global_load_dwordx4 v[68:71], v[156:157], off offset:1152
	ds_read_b128 v[112:115], v192
	ds_read_b128 v[120:123], v192 offset:32
	ds_read_b128 v[140:143], v192 offset:4608
	ds_read_b128 v[144:147], v192 offset:4640
	ds_read_b128 v[174:177], v191 offset:36864
	ds_read_b128 v[178:181], v191 offset:36896
	ds_read_b128 v[206:209], v191 offset:41472
	ds_read_b128 v[210:213], v191 offset:41504
	s_waitcnt lgkmcnt(3)
	v_mfma_f32_32x32x16_bf16 v[52:67], v[112:115], v[174:177], v[52:67]
	s_waitcnt lgkmcnt(1)
	v_mfma_f32_32x32x16_bf16 v[36:51], v[112:115], v[206:209], v[36:51]
	v_mfma_f32_32x32x16_bf16 v[4:19], v[140:143], v[206:209], v[4:19]
	s_waitcnt lgkmcnt(0)
	v_mfma_f32_32x32x16_bf16 v[36:51], v[120:123], v[210:213], v[36:51]
	v_mfma_f32_32x32x16_bf16 v[4:19], v[144:147], v[210:213], v[4:19]
	ds_read_b128 v[210:213], v191 offset:41568
	ds_read_b128 v[112:115], v192 offset:4672
	v_mfma_f32_32x32x16_bf16 v[20:35], v[140:143], v[174:177], v[20:35]
	ds_read_b128 v[174:177], v192 offset:4704
	ds_read_b128 v[140:143], v192 offset:64
	v_mfma_f32_32x32x16_bf16 v[52:67], v[120:123], v[178:181], v[52:67]
	ds_read_b128 v[206:209], v191 offset:36960
	ds_read_b128 v[120:123], v191 offset:41536
	v_mfma_f32_32x32x16_bf16 v[20:35], v[144:147], v[178:181], v[20:35]
	ds_read_b128 v[178:181], v191 offset:36928
	ds_read_b128 v[144:147], v192 offset:96
	s_waitcnt lgkmcnt(1)
	v_mfma_f32_32x32x16_bf16 v[52:67], v[140:143], v[178:181], v[52:67]
	s_waitcnt vmcnt(15)
	ds_write_b128 v198, v[132:135]
	v_mfma_f32_32x32x16_bf16 v[36:51], v[140:143], v[120:123], v[36:51]
	s_waitcnt vmcnt(14)
	ds_write_b128 v198, v[124:127] offset:36864
	v_mfma_f32_32x32x16_bf16 v[20:35], v[112:115], v[178:181], v[20:35]
	s_waitcnt vmcnt(13)
	ds_write_b128 v196, v[108:111]
	v_mfma_f32_32x32x16_bf16 v[4:19], v[112:115], v[120:123], v[4:19]
	s_setprio 0
	s_waitcnt vmcnt(12)
	ds_write_b128 v196, v[100:103] offset:36864
	s_waitcnt lgkmcnt(4)
	v_mfma_f32_32x32x16_bf16 v[52:67], v[144:147], v[206:209], v[52:67]
	s_waitcnt vmcnt(11)
	ds_write_b128 v194, v[96:99]
	v_mfma_f32_32x32x16_bf16 v[36:51], v[144:147], v[210:213], v[36:51]
	s_waitcnt vmcnt(10)
	ds_write_b128 v194, v[88:91] offset:36864
	v_mfma_f32_32x32x16_bf16 v[20:35], v[174:177], v[206:209], v[20:35]
	s_waitcnt vmcnt(9)
	ds_write_b128 v2, v[80:83]
	v_mfma_f32_32x32x16_bf16 v[4:19], v[174:177], v[210:213], v[4:19]
	s_waitcnt vmcnt(8)
	ds_write_b128 v2, v[72:75] offset:36864
	s_waitcnt lgkmcnt(0)
	s_barrier
; #define MFMA(a, b, c) __builtin_amdgcn_mfma_f32_32x32x16_bf16((a), (b), (c), 0, 0, 0)
; template <class Epi, class ColV>
; DI void gemm_tile(const bf16_t* __restrict__ A, int lda, const bf16_t* __restrict__ Bt, int ldb, int K, int m0, int n0, unsigned char* smem, Epi epi, ColV colv, const bf16_t* __restrict__ HYT = nullptr) {
;     ...
;     auto gload = [&](u32x4 (&r)[8], int kt) {
; #pragma unroll
;         for (int i = 0; i < 4; ++i) { int id = tid + 256 * i, row = id >> 3, kc = id & 7;
;     ...
;     auto step = [&](int kt, u32x4 (&ldset)[8], const u32x4 (&stset)[8]) {
;         const int buf = kt & 1;
;         if (kt + 2 < nk) gload(ldset, kt + 2);
;         const bf16_t* Ab = As + (buf * 128 + 64 * wr + li) * LS + 8 * lh;
;         const bf16_t* Bb = Bs + (buf * 128 + 64 * wc + li) * LS + 8 * lh;
;         bf16x8 fa[2][2], fb[2][2], ga[2][2], gb[2][2];
; #pragma unroll
;         for (int k2 = 0; k2 < 2; ++k2) { fa[k2][0] = ld8(Ab + 16 * k2); fa[k2][1] = ld8(Ab + 32 * LS + 16 * k2); fb[k2][0] = ld8(Bb + 16 * k2); fb[k2][1] = ld8(Bb + 32 * LS + 16 * k2); }
;         __builtin_amdgcn_sched_barrier(0);
; #pragma unroll
;         for (int k2 = 0; k2 < 2; ++k2) {
;             acc[0][0] = MFMA(fa[k2][0], fb[k2][0], acc[0][0]); acc[0][1] = MFMA(fa[k2][0], fb[k2][1], acc[0][1]);
;             acc[1][0] = MFMA(fa[k2][1], fb[k2][0], acc[1][0]); acc[1][1] = MFMA(fa[k2][1], fb[k2][1], acc[1][1]);
;         }
; #pragma unroll
;         for (int k2 = 0; k2 < 2; ++k2) { const int ks = 2 + k2; ga[k2][0] = ld8(Ab + 16 * ks); ga[k2][1] = ld8(Ab + 32 * LS + 16 * ks); gb[k2][0] = ld8(Bb + 16 * ks); gb[k2][1] = ld8(Bb + 32 * LS + 16 * ks); }
; #pragma unroll
;         for (int k2 = 0; k2 < 2; ++k2) {
;             acc[0][0] = MFMA(ga[k2][0], gb[k2][0], acc[0][0]); acc[0][1] = MFMA(ga[k2][0], gb[k2][1], acc[0][1]);
;             acc[1][0] = MFMA(ga[k2][1], gb[k2][0], acc[1][0]); acc[1][1] = MFMA(ga[k2][1], gb[k2][1], acc[1][1]);
;         }
;         if (kt + 1 < nk) sstore(stset, buf ^ 1, kt + 1);
; #pragma unroll
;         for (int i = 0; i < 8; ++i) { __builtin_amdgcn_sched_group_barrier(0x008, 1, 0); __builtin_amdgcn_sched_group_barrier(0x100, 1, 0); }
; #pragma unroll
;         for (int i = 0; i < 8; ++i) { __builtin_amdgcn_sched_group_barrier(0x008, 1, 0); __builtin_amdgcn_sched_group_barrier(0x200, 1, 0); }
;         __builtin_amdgcn_sched_barrier(0);
;         __syncthreads();
	s_setprio 1
	global_load_dwordx4 v[140:143], v[160:161], off offset:1280
	global_load_dwordx4 v[132:135], v[0:1], off offset:1280
	global_load_dwordx4 v[120:123], v[162:163], off offset:1280
	global_load_dwordx4 v[112:115], v[152:153], off offset:1280
	global_load_dwordx4 v[96:99], v[164:165], off offset:1280
	global_load_dwordx4 v[88:91], v[154:155], off offset:1280
	global_load_dwordx4 v[80:83], v[166:167], off offset:1280
	global_load_dwordx4 v[72:75], v[156:157], off offset:1280
	ds_read_b128 v[100:103], v201
	ds_read_b128 v[108:111], v201 offset:32
	ds_read_b128 v[124:127], v201 offset:4608
	ds_read_b128 v[144:147], v201 offset:4640
	ds_read_b128 v[174:177], v200 offset:36864
	ds_read_b128 v[178:181], v200 offset:36896
	ds_read_b128 v[206:209], v200 offset:41472
	ds_read_b128 v[210:213], v200 offset:41504
	s_waitcnt lgkmcnt(3)
	v_mfma_f32_32x32x16_bf16 v[52:67], v[100:103], v[174:177], v[52:67]
	s_waitcnt lgkmcnt(1)
	v_mfma_f32_32x32x16_bf16 v[36:51], v[100:103], v[206:209], v[36:51]
	v_mfma_f32_32x32x16_bf16 v[4:19], v[124:127], v[206:209], v[4:19]
	s_waitcnt lgkmcnt(0)
	v_mfma_f32_32x32x16_bf16 v[36:51], v[108:111], v[210:213], v[36:51]
	v_mfma_f32_32x32x16_bf16 v[4:19], v[144:147], v[210:213], v[4:19]
	ds_read_b128 v[210:213], v200 offset:41568
	ds_read_b128 v[100:103], v201 offset:4672
	v_mfma_f32_32x32x16_bf16 v[20:35], v[124:127], v[174:177], v[20:35]
	ds_read_b128 v[174:177], v201 offset:4704
	ds_read_b128 v[124:127], v201 offset:64
	v_mfma_f32_32x32x16_bf16 v[52:67], v[108:111], v[178:181], v[52:67]
	ds_read_b128 v[206:209], v200 offset:36960
	ds_read_b128 v[108:111], v200 offset:41536
	v_mfma_f32_32x32x16_bf16 v[20:35], v[144:147], v[178:181], v[20:35]
	ds_read_b128 v[178:181], v200 offset:36928
	ds_read_b128 v[144:147], v201 offset:96
	s_waitcnt lgkmcnt(1)
	v_mfma_f32_32x32x16_bf16 v[52:67], v[124:127], v[178:181], v[52:67]
	s_waitcnt vmcnt(15)
	ds_write_b128 v198, v[136:139] offset:18432
	v_mfma_f32_32x32x16_bf16 v[36:51], v[124:127], v[108:111], v[36:51]
	s_waitcnt vmcnt(14)
	ds_write_b128 v198, v[128:131] offset:55296
	v_mfma_f32_32x32x16_bf16 v[20:35], v[100:103], v[178:181], v[20:35]
	s_waitcnt vmcnt(13)
	ds_write_b128 v196, v[116:119] offset:18432
	v_mfma_f32_32x32x16_bf16 v[4:19], v[100:103], v[108:111], v[4:19]
	s_setprio 0
	s_waitcnt vmcnt(12)
	ds_write_b128 v196, v[104:107] offset:55296
	s_waitcnt lgkmcnt(4)
	v_mfma_f32_32x32x16_bf16 v[52:67], v[144:147], v[206:209], v[52:67]
	s_waitcnt vmcnt(11)
	ds_write_b128 v194, v[92:95] offset:18432
	v_mfma_f32_32x32x16_bf16 v[36:51], v[144:147], v[210:213], v[36:51]
	s_waitcnt vmcnt(10)
	ds_write_b128 v194, v[84:87] offset:55296
	v_mfma_f32_32x32x16_bf16 v[20:35], v[174:177], v[206:209], v[20:35]
	s_waitcnt vmcnt(9)
	ds_write_b128 v2, v[76:79] offset:18432
	v_mfma_f32_32x32x16_bf16 v[4:19], v[174:177], v[210:213], v[4:19]
	s_waitcnt vmcnt(8)
	ds_write_b128 v2, v[68:71] offset:55296
	s_waitcnt lgkmcnt(0)
	s_barrier
	s_setprio 1
	global_load_dwordx4 v[124:127], v[160:161], off offset:1408
	global_load_dwordx4 v[116:119], v[0:1], off offset:1408
	global_load_dwordx4 v[108:111], v[162:163], off offset:1408
	global_load_dwordx4 v[100:103], v[152:153], off offset:1408
	global_load_dwordx4 v[92:95], v[164:165], off offset:1408
	global_load_dwordx4 v[84:87], v[154:155], off offset:1408
	global_load_dwordx4 v[76:79], v[166:167], off offset:1408
	global_load_dwordx4 v[68:71], v[156:157], off offset:1408
	ds_read_b128 v[104:107], v192
	ds_read_b128 v[128:131], v192 offset:32
	ds_read_b128 v[136:139], v192 offset:4608
	ds_read_b128 v[144:147], v192 offset:4640
	ds_read_b128 v[160:163], v191 offset:36864
	ds_read_b128 v[164:167], v191 offset:36896
	ds_read_b128 v[174:177], v191 offset:41472
	ds_read_b128 v[178:181], v191 offset:41504
	s_waitcnt lgkmcnt(3)
	v_mfma_f32_32x32x16_bf16 v[52:67], v[104:107], v[160:163], v[52:67]
	s_waitcnt lgkmcnt(1)
	v_mfma_f32_32x32x16_bf16 v[36:51], v[104:107], v[174:177], v[36:51]
	v_mfma_f32_32x32x16_bf16 v[4:19], v[136:139], v[174:177], v[4:19]
	s_waitcnt lgkmcnt(0)
	v_mfma_f32_32x32x16_bf16 v[36:51], v[128:131], v[178:181], v[36:51]
	v_mfma_f32_32x32x16_bf16 v[4:19], v[144:147], v[178:181], v[4:19]
	ds_read_b128 v[178:181], v191 offset:41568
	ds_read_b128 v[104:107], v192 offset:4672
	v_mfma_f32_32x32x16_bf16 v[20:35], v[136:139], v[160:163], v[20:35]
	ds_read_b128 v[160:163], v192 offset:4704
	ds_read_b128 v[136:139], v192 offset:64
	v_mfma_f32_32x32x16_bf16 v[52:67], v[128:131], v[164:167], v[52:67]
	ds_read_b128 v[174:177], v191 offset:36960
	ds_read_b128 v[128:131], v191 offset:41536
	v_mfma_f32_32x32x16_bf16 v[20:35], v[144:147], v[164:167], v[20:35]
	ds_read_b128 v[164:167], v191 offset:36928
	ds_read_b128 v[144:147], v192 offset:96
	s_waitcnt lgkmcnt(1)
	v_mfma_f32_32x32x16_bf16 v[52:67], v[136:139], v[164:167], v[52:67]
	s_waitcnt vmcnt(15)
	ds_write_b128 v198, v[140:143]
	v_mfma_f32_32x32x16_bf16 v[36:51], v[136:139], v[128:131], v[36:51]
	s_waitcnt vmcnt(14)
	ds_write_b128 v198, v[132:135] offset:36864
	v_mfma_f32_32x32x16_bf16 v[20:35], v[104:107], v[164:167], v[20:35]
	s_waitcnt vmcnt(13)
	ds_write_b128 v196, v[120:123]
	v_mfma_f32_32x32x16_bf16 v[4:19], v[104:107], v[128:131], v[4:19]
	s_setprio 0
	s_waitcnt vmcnt(12)
	ds_write_b128 v196, v[112:115] offset:36864
	s_waitcnt lgkmcnt(4)
	v_mfma_f32_32x32x16_bf16 v[52:67], v[144:147], v[174:177], v[52:67]
	s_waitcnt vmcnt(11)
	ds_write_b128 v194, v[96:99]
	v_mfma_f32_32x32x16_bf16 v[36:51], v[144:147], v[178:181], v[36:51]
	s_waitcnt vmcnt(10)
	ds_write_b128 v194, v[88:91] offset:36864
	v_mfma_f32_32x32x16_bf16 v[20:35], v[160:163], v[174:177], v[20:35]
	s_waitcnt vmcnt(9)
	ds_write_b128 v2, v[80:83]
	v_mfma_f32_32x32x16_bf16 v[4:19], v[160:163], v[178:181], v[4:19]
	s_waitcnt vmcnt(8)
	ds_write_b128 v2, v[72:75] offset:36864
	v_mad_i64_i32 v[96:97], s[40:41], v202, s43, v[158:159]
	v_mad_i64_i32 v[98:99], s[40:41], v205, s43, v[158:159]
	v_mad_i64_i32 v[112:113], s[40:41], v204, s43, v[158:159]
	v_mad_i64_i32 v[132:133], s[40:41], v203, s43, v[158:159]
	s_waitcnt lgkmcnt(0)
	s_barrier
; #define MFMA(a, b, c) __builtin_amdgcn_mfma_f32_32x32x16_bf16((a), (b), (c), 0, 0, 0)
; template <class Epi, class ColV>
; DI void gemm_tile(const bf16_t* __restrict__ A, int lda, const bf16_t* __restrict__ Bt, int ldb, int K, int m0, int n0, unsigned char* smem, Epi epi, ColV colv, const bf16_t* __restrict__ HYT = nullptr) {
;     ...
;     auto gload = [&](u32x4 (&r)[8], int kt) {
; #pragma unroll
;         for (int i = 0; i < 4; ++i) { int id = tid + 256 * i, row = id >> 3, kc = id & 7;
;             if (HYT && kt >= 12) r[i] = *(const u32x4*)(HYT + (size_t)((kt - 12) * 64 + (id >> 4)) * NT + m0 + (id & 15) * 8);
;             else r[i] = *(const u32x4*)(A + (size_t)(m0 + row) * lda + kt * 64 + kc * 8);
;             r[4 + i] = *(const u32x4*)(Bt + (size_t)(n0 + row) * ldb + kt * 64 + kc * 8); }
;     };
;     auto sstore = [&](const u32x4 (&r)[8], int buf, int kt) {
; #pragma unroll
;         for (int i = 0; i < 4; ++i) { int id = tid + 256 * i, row = id >> 3, kc = id & 7;
;             if (HYT && kt >= 12) { const int kk = id >> 4, rr = (id & 15) * 8; bf16_t* d = As + (buf * 128 + rr) * LS + kk; const bf16x8 v = __builtin_bit_cast(bf16x8, r[i]);
; #pragma unroll
;                 for (int e = 0; e < 8; ++e) d[e * LS] = (bf16_t)v[e]; }
;             else *(u32x4*)(As + (buf * 128 + row) * LS + kc * 8) = r[i];
;             *(u32x4*)(Bs + (buf * 128 + row) * LS + kc * 8) = r[4 + i]; }
;     };
;     auto step = [&](int kt, u32x4 (&ldset)[8], const u32x4 (&stset)[8]) {
;         const int buf = kt & 1;
;         if (kt + 2 < nk) gload(ldset, kt + 2);
;         const bf16_t* Ab = As + (buf * 128 + 64 * wr + li) * LS + 8 * lh;
;         const bf16_t* Bb = Bs + (buf * 128 + 64 * wc + li) * LS + 8 * lh;
;         bf16x8 fa[2][2], fb[2][2], ga[2][2], gb[2][2];
; #pragma unroll
;         for (int k2 = 0; k2 < 2; ++k2) { fa[k2][0] = ld8(Ab + 16 * k2); fa[k2][1] = ld8(Ab + 32 * LS + 16 * k2); fb[k2][0] = ld8(Bb + 16 * k2); fb[k2][1] = ld8(Bb + 32 * LS + 16 * k2); }
;         __builtin_amdgcn_sched_barrier(0);
; #pragma unroll
;         for (int k2 = 0; k2 < 2; ++k2) {
;             acc[0][0] = MFMA(fa[k2][0], fb[k2][0], acc[0][0]); acc[0][1] = MFMA(fa[k2][0], fb[k2][1], acc[0][1]);
;             acc[1][0] = MFMA(fa[k2][1], fb[k2][0], acc[1][0]); acc[1][1] = MFMA(fa[k2][1], fb[k2][1], acc[1][1]);
;         }
; #pragma unroll
	s_setprio 1
	global_load_dwordx4 v[104:107], v[0:1], off offset:1536
	global_load_dwordx4 v[88:91], v[152:153], off offset:1536
	global_load_dwordx4 v[80:83], v[154:155], off offset:1536
	global_load_dwordx4 v[72:75], v[156:157], off offset:1536
	global_load_dwordx4 v[128:131], v[96:97], off
	global_load_dwordx4 v[120:123], v[98:99], off offset:16
	ds_read_b128 v[136:139], v201 offset:32
	global_load_dwordx4 v[112:115], v[112:113], off offset:32
	ds_read_b128 v[140:143], v201 offset:4608
	global_load_dwordx4 v[96:99], v[132:133], off offset:48
	ds_read_b128 v[132:135], v201
	ds_read_b128 v[144:147], v201 offset:4640
	ds_read_b128 v[160:163], v200 offset:36864
	ds_read_b128 v[164:167], v200 offset:36896
	ds_read_b128 v[174:177], v200 offset:41472
	ds_read_b128 v[178:181], v200 offset:41504
	s_waitcnt lgkmcnt(3)
	v_mfma_f32_32x32x16_bf16 v[52:67], v[132:135], v[160:163], v[52:67]
	s_waitcnt lgkmcnt(1)
	v_mfma_f32_32x32x16_bf16 v[36:51], v[132:135], v[174:177], v[36:51]
	v_mfma_f32_32x32x16_bf16 v[4:19], v[140:143], v[174:177], v[4:19]
	s_waitcnt lgkmcnt(0)
	v_mfma_f32_32x32x16_bf16 v[36:51], v[136:139], v[178:181], v[36:51]
	v_mfma_f32_32x32x16_bf16 v[4:19], v[144:147], v[178:181], v[4:19]
	ds_read_b128 v[178:181], v200 offset:41568
	ds_read_b128 v[132:135], v201 offset:4672
	v_mfma_f32_32x32x16_bf16 v[20:35], v[140:143], v[160:163], v[20:35]
	ds_read_b128 v[160:163], v201 offset:4704
	ds_read_b128 v[140:143], v201 offset:64
	v_mfma_f32_32x32x16_bf16 v[52:67], v[136:139], v[164:167], v[52:67]
	ds_read_b128 v[174:177], v200 offset:36960
	ds_read_b128 v[136:139], v200 offset:41536
	v_mfma_f32_32x32x16_bf16 v[20:35], v[144:147], v[164:167], v[20:35]
	ds_read_b128 v[164:167], v200 offset:36928
	ds_read_b128 v[144:147], v201 offset:96
	s_waitcnt lgkmcnt(1)
	v_mfma_f32_32x32x16_bf16 v[52:67], v[140:143], v[164:167], v[52:67]
	s_waitcnt vmcnt(15)
	ds_write_b128 v198, v[124:127] offset:18432
	v_mfma_f32_32x32x16_bf16 v[36:51], v[140:143], v[136:139], v[36:51]
	s_waitcnt vmcnt(14)
	ds_write_b128 v198, v[116:119] offset:55296
	v_mfma_f32_32x32x16_bf16 v[20:35], v[132:135], v[164:167], v[20:35]
	s_waitcnt vmcnt(13)
	ds_write_b128 v196, v[108:111] offset:18432
	v_mfma_f32_32x32x16_bf16 v[4:19], v[132:135], v[136:139], v[4:19]
	s_setprio 0
	s_waitcnt vmcnt(12)
	ds_write_b128 v196, v[100:103] offset:55296
	s_waitcnt lgkmcnt(4)
	v_mfma_f32_32x32x16_bf16 v[52:67], v[144:147], v[174:177], v[52:67]
	s_waitcnt vmcnt(11)
	ds_write_b128 v194, v[92:95] offset:18432
	v_mfma_f32_32x32x16_bf16 v[36:51], v[144:147], v[178:181], v[36:51]
	s_waitcnt vmcnt(10)
	ds_write_b128 v194, v[84:87] offset:55296
	v_mfma_f32_32x32x16_bf16 v[20:35], v[160:163], v[174:177], v[20:35]
	s_waitcnt vmcnt(9)
	ds_write_b128 v2, v[76:79] offset:18432
	v_mfma_f32_32x32x16_bf16 v[4:19], v[160:163], v[178:181], v[4:19]
	s_waitcnt vmcnt(8)
	ds_write_b128 v2, v[68:71] offset:55296
	v_add_u32_e32 v68, 64, v202
	v_mad_i64_i32 v[92:93], s[40:41], v68, s43, v[158:159]
	v_add_u32_e32 v68, 64, v205
	v_mad_i64_i32 v[94:95], s[40:41], v68, s43, v[158:159]
	v_add_u32_e32 v68, 64, v204
	v_mad_i64_i32 v[108:109], s[40:41], v68, s43, v[158:159]
	v_add_u32_e32 v68, 64, v203
	v_mad_i64_i32 v[132:133], s[40:41], v68, s43, v[158:159]
	s_waitcnt lgkmcnt(0)
	s_barrier
	s_setprio 1
	global_load_dwordx4 v[100:103], v[0:1], off offset:1664
	global_load_dwordx4 v[84:87], v[152:153], off offset:1664
	global_load_dwordx4 v[76:79], v[154:155], off offset:1664
	global_load_dwordx4 v[68:71], v[156:157], off offset:1664
	global_load_dwordx4 v[124:127], v[92:93], off
	global_load_dwordx4 v[116:119], v[94:95], off offset:16
	ds_read_b128 v[136:139], v192 offset:32
	global_load_dwordx4 v[108:111], v[108:109], off offset:32
	ds_read_b128 v[140:143], v192 offset:4608
	global_load_dwordx4 v[92:95], v[132:133], off offset:48
	ds_read_b128 v[132:135], v192
	ds_read_b128 v[144:147], v192 offset:4640
	ds_read_b128 v[160:163], v191 offset:36864
	ds_read_b128 v[164:167], v191 offset:36896
	ds_read_b128 v[174:177], v191 offset:41472
	ds_read_b128 v[178:181], v191 offset:41504
	s_waitcnt lgkmcnt(3)
	v_mfma_f32_32x32x16_bf16 v[52:67], v[132:135], v[160:163], v[52:67]
	s_waitcnt lgkmcnt(1)
	v_mfma_f32_32x32x16_bf16 v[36:51], v[132:135], v[174:177], v[36:51]
	v_mfma_f32_32x32x16_bf16 v[4:19], v[140:143], v[174:177], v[4:19]
	s_waitcnt lgkmcnt(0)
	v_mfma_f32_32x32x16_bf16 v[36:51], v[136:139], v[178:181], v[36:51]
	v_mfma_f32_32x32x16_bf16 v[4:19], v[144:147], v[178:181], v[4:19]
	ds_read_b128 v[178:181], v191 offset:41568
	ds_read_b128 v[132:135], v192 offset:4672
	v_mfma_f32_32x32x16_bf16 v[20:35], v[140:143], v[160:163], v[20:35]
	ds_read_b128 v[160:163], v192 offset:4704
	ds_read_b128 v[140:143], v192 offset:64
	v_mfma_f32_32x32x16_bf16 v[52:67], v[136:139], v[164:167], v[52:67]
	ds_read_b128 v[174:177], v191 offset:36960
	ds_read_b128 v[136:139], v191 offset:41536
	v_mfma_f32_32x32x16_bf16 v[20:35], v[144:147], v[164:167], v[20:35]
	ds_read_b128 v[164:167], v191 offset:36928
	ds_read_b128 v[144:147], v192 offset:96
	s_waitcnt lgkmcnt(1)
	v_mfma_f32_32x32x16_bf16 v[52:67], v[140:143], v[164:167], v[52:67]
	s_waitcnt vmcnt(11)
	ds_write_b16 v199, v128
	v_mfma_f32_32x32x16_bf16 v[36:51], v[140:143], v[136:139], v[36:51]
	ds_write_b16_d16_hi v199, v128 offset:144
	v_mfma_f32_32x32x16_bf16 v[20:35], v[132:135], v[164:167], v[20:35]
	ds_write_b16 v199, v129 offset:288
	v_mfma_f32_32x32x16_bf16 v[4:19], v[132:135], v[136:139], v[4:19]
	s_setprio 0
	ds_write_b16_d16_hi v199, v129 offset:432
	s_waitcnt lgkmcnt(4)
; #define MFMA(a, b, c) __builtin_amdgcn_mfma_f32_32x32x16_bf16((a), (b), (c), 0, 0, 0)
; template <class Epi, class ColV>
; DI void gemm_tile(const bf16_t* __restrict__ A, int lda, const bf16_t* __restrict__ Bt, int ldb, int K, int m0, int n0, unsigned char* smem, Epi epi, ColV colv, const bf16_t* __restrict__ HYT = nullptr) {
;     ...
;     auto gload = [&](u32x4 (&r)[8], int kt) {
; #pragma unroll
;         for (int i = 0; i < 4; ++i) { int id = tid + 256 * i, row = id >> 3, kc = id & 7;
;             if (HYT && kt >= 12) r[i] = *(const u32x4*)(HYT + (size_t)((kt - 12) * 64 + (id >> 4)) * NT + m0 + (id & 15) * 8);
;             else r[i] = *(const u32x4*)(A + (size_t)(m0 + row) * lda + kt * 64 + kc * 8);
;             r[4 + i] = *(const u32x4*)(Bt + (size_t)(n0 + row) * ldb + kt * 64 + kc * 8); }
;     };
;     auto sstore = [&](const u32x4 (&r)[8], int buf, int kt) {
; #pragma unroll
;         for (int i = 0; i < 4; ++i) { int id = tid + 256 * i, row = id >> 3, kc = id & 7;
;             if (HYT && kt >= 12) { const int kk = id >> 4, rr = (id & 15) * 8; bf16_t* d = As + (buf * 128 + rr) * LS + kk; const bf16x8 v = __builtin_bit_cast(bf16x8, r[i]);
; #pragma unroll
;                 for (int e = 0; e < 8; ++e) d[e * LS] = (bf16_t)v[e]; }
;             else *(u32x4*)(As + (buf * 128 + row) * LS + kc * 8) = r[i];
;             *(u32x4*)(Bs + (buf * 128 + row) * LS + kc * 8) = r[4 + i]; }
;     };
;     auto step = [&](int kt, u32x4 (&ldset)[8], const u32x4 (&stset)[8]) {
;         const int buf = kt & 1;
;         if (kt + 2 < nk) gload(ldset, kt + 2);
;         const bf16_t* Ab = As + (buf * 128 + 64 * wr + li) * LS + 8 * lh;
;         const bf16_t* Bb = Bs + (buf * 128 + 64 * wc + li) * LS + 8 * lh;
;         bf16x8 fa[2][2], fb[2][2], ga[2][2], gb[2][2];
; #pragma unroll
;         for (int k2 = 0; k2 < 2; ++k2) { fa[k2][0] = ld8(Ab + 16 * k2); fa[k2][1] = ld8(Ab + 32 * LS + 16 * k2); fb[k2][0] = ld8(Bb + 16 * k2); fb[k2][1] = ld8(Bb + 32 * LS + 16 * k2); }
;         __builtin_amdgcn_sched_barrier(0);
; #pragma unroll
;         for (int k2 = 0; k2 < 2; ++k2) {
;             acc[0][0] = MFMA(fa[k2][0], fb[k2][0], acc[0][0]); acc[0][1] = MFMA(fa[k2][0], fb[k2][1], acc[0][1]);
;             acc[1][0] = MFMA(fa[k2][1], fb[k2][0], acc[1][0]); acc[1][1] = MFMA(fa[k2][1], fb[k2][1], acc[1][1]);
;         }
; #pragma unroll
	v_mfma_f32_32x32x16_bf16 v[52:67], v[144:147], v[174:177], v[52:67]
	ds_write_b16 v199, v130 offset:576
	v_mfma_f32_32x32x16_bf16 v[36:51], v[144:147], v[178:181], v[36:51]
	ds_write_b16_d16_hi v199, v130 offset:720
	v_mfma_f32_32x32x16_bf16 v[20:35], v[160:163], v[174:177], v[20:35]
	ds_write_b16 v199, v131 offset:864
	v_mfma_f32_32x32x16_bf16 v[4:19], v[160:163], v[178:181], v[4:19]
	ds_write_b16_d16_hi v199, v131 offset:1008
	ds_write_b128 v198, v[104:107] offset:36864
	s_waitcnt vmcnt(10)
	ds_write_b16 v197, v120 offset:1152
	ds_write_b16_d16_hi v197, v120 offset:1296
	ds_write_b16 v197, v121 offset:1440
	ds_write_b16_d16_hi v197, v121 offset:1584
	ds_write_b16 v197, v122 offset:1728
	ds_write_b16_d16_hi v197, v122 offset:1872
	ds_write_b16 v197, v123 offset:2016
	ds_write_b16_d16_hi v197, v123 offset:2160
	ds_write_b128 v196, v[88:91] offset:36864
	s_waitcnt vmcnt(9)
	ds_write_b16 v195, v112 offset:2304
	ds_write_b16_d16_hi v195, v112 offset:2448
	ds_write_b16 v195, v113 offset:2592
	ds_write_b16_d16_hi v195, v113 offset:2736
	ds_write_b16 v195, v114 offset:2880
	ds_write_b16_d16_hi v195, v114 offset:3024
	ds_write_b16 v195, v115 offset:3168
	ds_write_b16_d16_hi v195, v115 offset:3312
	ds_write_b128 v194, v[80:83] offset:36864
	s_waitcnt vmcnt(8)
	ds_write_b16 v193, v96 offset:3456
	ds_write_b16_d16_hi v193, v96 offset:3600
	ds_write_b16 v193, v97 offset:3744
	ds_write_b16_d16_hi v193, v97 offset:3888
	ds_write_b16 v193, v98 offset:4032
	ds_write_b16_d16_hi v193, v98 offset:4176
	ds_write_b16 v193, v99 offset:4320
	ds_write_b16_d16_hi v193, v99 offset:4464
	ds_write_b128 v2, v[72:75] offset:36864
	v_add_u32_e32 v72, 0x80, v202
	v_mad_i64_i32 v[96:97], s[40:41], v72, s43, v[158:159]
	v_add_u32_e32 v72, 0x80, v205
	v_mad_i64_i32 v[98:99], s[40:41], v72, s43, v[158:159]
	v_add_u32_e32 v72, 0x80, v204
	v_mad_i64_i32 v[112:113], s[40:41], v72, s43, v[158:159]
	v_add_u32_e32 v72, 0x80, v203
	v_mad_i64_i32 v[132:133], s[40:41], v72, s43, v[158:159]
	s_waitcnt lgkmcnt(0)
	s_barrier
	s_setprio 1
	global_load_dwordx4 v[104:107], v[0:1], off offset:1792
	global_load_dwordx4 v[88:91], v[152:153], off offset:1792
	global_load_dwordx4 v[80:83], v[154:155], off offset:1792
	global_load_dwordx4 v[72:75], v[156:157], off offset:1792
	global_load_dwordx4 v[128:131], v[96:97], off
	global_load_dwordx4 v[120:123], v[98:99], off offset:16
	ds_read_b128 v[136:139], v201 offset:32
	global_load_dwordx4 v[112:115], v[112:113], off offset:32
	ds_read_b128 v[140:143], v201 offset:4608
	global_load_dwordx4 v[96:99], v[132:133], off offset:48
	ds_read_b128 v[132:135], v201
	ds_read_b128 v[144:147], v201 offset:4640
	ds_read_b128 v[160:163], v200 offset:36864
	ds_read_b128 v[164:167], v200 offset:36896
	ds_read_b128 v[174:177], v200 offset:41472
	ds_read_b128 v[178:181], v200 offset:41504
	s_waitcnt lgkmcnt(3)
	v_mfma_f32_32x32x16_bf16 v[52:67], v[132:135], v[160:163], v[52:67]
	s_waitcnt lgkmcnt(1)
	v_mfma_f32_32x32x16_bf16 v[36:51], v[132:135], v[174:177], v[36:51]
	v_mfma_f32_32x32x16_bf16 v[4:19], v[140:143], v[174:177], v[4:19]
	s_waitcnt lgkmcnt(0)
	v_mfma_f32_32x32x16_bf16 v[36:51], v[136:139], v[178:181], v[36:51]
	v_mfma_f32_32x32x16_bf16 v[4:19], v[144:147], v[178:181], v[4:19]
	ds_read_b128 v[178:181], v200 offset:41568
	ds_read_b128 v[132:135], v201 offset:4672
	v_mfma_f32_32x32x16_bf16 v[20:35], v[140:143], v[160:163], v[20:35]
	ds_read_b128 v[160:163], v201 offset:4704
	ds_read_b128 v[140:143], v201 offset:64
	v_mfma_f32_32x32x16_bf16 v[52:67], v[136:139], v[164:167], v[52:67]
	ds_read_b128 v[174:177], v200 offset:36960
	ds_read_b128 v[136:139], v200 offset:41536
	v_mfma_f32_32x32x16_bf16 v[20:35], v[144:147], v[164:167], v[20:35]
	ds_read_b128 v[164:167], v200 offset:36928
	ds_read_b128 v[144:147], v201 offset:96
	s_waitcnt lgkmcnt(1)
	v_mfma_f32_32x32x16_bf16 v[52:67], v[140:143], v[164:167], v[52:67]
	s_waitcnt vmcnt(11)
	ds_write_b16 v199, v124 offset:18432
	v_mfma_f32_32x32x16_bf16 v[36:51], v[140:143], v[136:139], v[36:51]
	ds_write_b16_d16_hi v199, v124 offset:18576
	v_mfma_f32_32x32x16_bf16 v[20:35], v[132:135], v[164:167], v[20:35]
	ds_write_b16 v199, v125 offset:18720
	v_mfma_f32_32x32x16_bf16 v[4:19], v[132:135], v[136:139], v[4:19]
	s_setprio 0
	ds_write_b16_d16_hi v199, v125 offset:18864
	s_waitcnt lgkmcnt(4)
	v_mfma_f32_32x32x16_bf16 v[52:67], v[144:147], v[174:177], v[52:67]
	ds_write_b16 v199, v126 offset:19008
	v_mfma_f32_32x32x16_bf16 v[36:51], v[144:147], v[178:181], v[36:51]
	ds_write_b16_d16_hi v199, v126 offset:19152
	v_mfma_f32_32x32x16_bf16 v[20:35], v[160:163], v[174:177], v[20:35]
	ds_write_b16 v199, v127 offset:19296
	v_mfma_f32_32x32x16_bf16 v[4:19], v[160:163], v[178:181], v[4:19]
	ds_write_b16_d16_hi v199, v127 offset:19440
	ds_write_b128 v198, v[100:103] offset:55296
	s_waitcnt vmcnt(10)
	ds_write_b16 v197, v116 offset:19584
	ds_write_b16_d16_hi v197, v116 offset:19728
	ds_write_b16 v197, v117 offset:19872
	ds_write_b16_d16_hi v197, v117 offset:20016
	ds_write_b16 v197, v118 offset:20160
	ds_write_b16_d16_hi v197, v118 offset:20304
	ds_write_b16 v197, v119 offset:20448
	ds_write_b16_d16_hi v197, v119 offset:20592
	ds_write_b128 v196, v[84:87] offset:55296
	s_waitcnt vmcnt(9)
	ds_write_b16 v195, v108 offset:20736
	ds_write_b16_d16_hi v195, v108 offset:20880
	ds_write_b16 v195, v109 offset:21024
	ds_write_b16_d16_hi v195, v109 offset:21168
	ds_write_b16 v195, v110 offset:21312
	ds_write_b16_d16_hi v195, v110 offset:21456
	ds_write_b16 v195, v111 offset:21600
	ds_write_b16_d16_hi v195, v111 offset:21744
	ds_write_b128 v194, v[76:79] offset:55296
	s_waitcnt vmcnt(8)
	ds_write_b16 v193, v92 offset:21888
	ds_write_b16_d16_hi v193, v92 offset:22032
	ds_write_b16 v193, v93 offset:22176
	ds_write_b16_d16_hi v193, v93 offset:22320
	ds_write_b16 v193, v94 offset:22464
	ds_write_b16_d16_hi v193, v94 offset:22608
	ds_write_b16 v193, v95 offset:22752
	ds_write_b16_d16_hi v193, v95 offset:22896
	ds_write_b128 v2, v[68:71] offset:55296
	v_add_u32_e32 v68, 0xc0, v202
	v_mad_i64_i32 v[92:93], s[40:41], v68, s43, v[158:159]
	v_add_u32_e32 v68, 0xc0, v205
	s_waitcnt lgkmcnt(0)
	s_barrier
; #define MFMA(a, b, c) __builtin_amdgcn_mfma_f32_32x32x16_bf16((a), (b), (c), 0, 0, 0)
; template <class Epi, class ColV>
; DI void gemm_tile(const bf16_t* __restrict__ A, int lda, const bf16_t* __restrict__ Bt, int ldb, int K, int m0, int n0, unsigned char* smem, Epi epi, ColV colv, const bf16_t* __restrict__ HYT = nullptr) {
;     ...
;     auto gload = [&](u32x4 (&r)[8], int kt) {
; #pragma unroll
;         for (int i = 0; i < 4; ++i) { int id = tid + 256 * i, row = id >> 3, kc = id & 7;
;             if (HYT && kt >= 12) r[i] = *(const u32x4*)(HYT + (size_t)((kt - 12) * 64 + (id >> 4)) * NT + m0 + (id & 15) * 8);
;             else r[i] = *(const u32x4*)(A + (size_t)(m0 + row) * lda + kt * 64 + kc * 8);
;             r[4 + i] = *(const u32x4*)(Bt + (size_t)(n0 + row) * ldb + kt * 64 + kc * 8); }
;     };
;     auto sstore = [&](const u32x4 (&r)[8], int buf, int kt) {
; #pragma unroll
;         for (int i = 0; i < 4; ++i) { int id = tid + 256 * i, row = id >> 3, kc = id & 7;
;             if (HYT && kt >= 12) { const int kk = id >> 4, rr = (id & 15) * 8; bf16_t* d = As + (buf * 128 + rr) * LS + kk; const bf16x8 v = __builtin_bit_cast(bf16x8, r[i]);
; #pragma unroll
;                 for (int e = 0; e < 8; ++e) d[e * LS] = (bf16_t)v[e]; }
;             else *(u32x4*)(As + (buf * 128 + row) * LS + kc * 8) = r[i];
;             *(u32x4*)(Bs + (buf * 128 + row) * LS + kc * 8) = r[4 + i]; }
;     };
;     auto step = [&](int kt, u32x4 (&ldset)[8], const u32x4 (&stset)[8]) {
;         const int buf = kt & 1;
;         if (kt + 2 < nk) gload(ldset, kt + 2);
;         const bf16_t* Ab = As + (buf * 128 + 64 * wr + li) * LS + 8 * lh;
;         const bf16_t* Bb = Bs + (buf * 128 + 64 * wc + li) * LS + 8 * lh;
;         bf16x8 fa[2][2], fb[2][2], ga[2][2], gb[2][2];
; #pragma unroll
;         for (int k2 = 0; k2 < 2; ++k2) { fa[k2][0] = ld8(Ab + 16 * k2); fa[k2][1] = ld8(Ab + 32 * LS + 16 * k2); fb[k2][0] = ld8(Bb + 16 * k2); fb[k2][1] = ld8(Bb + 32 * LS + 16 * k2); }
;         __builtin_amdgcn_sched_barrier(0);
; #pragma unroll
;         for (int k2 = 0; k2 < 2; ++k2) {
;             acc[0][0] = MFMA(fa[k2][0], fb[k2][0], acc[0][0]); acc[0][1] = MFMA(fa[k2][0], fb[k2][1], acc[0][1]);
;             acc[1][0] = MFMA(fa[k2][1], fb[k2][0], acc[1][0]); acc[1][1] = MFMA(fa[k2][1], fb[k2][1], acc[1][1]);
;         }
; #pragma unroll
	s_setprio 1
	v_mad_i64_i32 v[94:95], s[40:41], v68, s43, v[158:159]
	global_load_dwordx4 v[100:103], v[0:1], off offset:1920
	v_add_u32_e32 v0, 0xc0, v204
	v_add_u32_e32 v68, 0xc0, v203
	v_mad_i64_i32 v[0:1], s[40:41], v0, s43, v[158:159]
	v_mad_i64_i32 v[132:133], s[40:41], v68, s43, v[158:159]
	global_load_dwordx4 v[84:87], v[152:153], off offset:1920
	global_load_dwordx4 v[76:79], v[154:155], off offset:1920
	global_load_dwordx4 v[68:71], v[156:157], off offset:1920
	global_load_dwordx4 v[124:127], v[92:93], off
	global_load_dwordx4 v[116:119], v[94:95], off offset:16
	global_load_dwordx4 v[108:111], v[0:1], off offset:32
	ds_read_b128 v[136:139], v192 offset:32
	global_load_dwordx4 v[92:95], v[132:133], off offset:48
	ds_read_b128 v[132:135], v192
	ds_read_b128 v[140:143], v192 offset:4608
	ds_read_b128 v[144:147], v192 offset:4640
	ds_read_b128 v[152:155], v191 offset:36864
	ds_read_b128 v[156:159], v191 offset:36896
	ds_read_b128 v[160:163], v191 offset:41472
	ds_read_b128 v[164:167], v191 offset:41504
	s_waitcnt lgkmcnt(3)
	v_mfma_f32_32x32x16_bf16 v[52:67], v[132:135], v[152:155], v[52:67]
	s_waitcnt lgkmcnt(1)
	v_mfma_f32_32x32x16_bf16 v[36:51], v[132:135], v[160:163], v[36:51]
	v_mfma_f32_32x32x16_bf16 v[4:19], v[140:143], v[160:163], v[4:19]
	s_waitcnt lgkmcnt(0)
	v_mfma_f32_32x32x16_bf16 v[36:51], v[136:139], v[164:167], v[36:51]
	v_mfma_f32_32x32x16_bf16 v[4:19], v[144:147], v[164:167], v[4:19]
	ds_read_b128 v[164:167], v191 offset:41568
	ds_read_b128 v[132:135], v192 offset:4672
	v_mfma_f32_32x32x16_bf16 v[20:35], v[140:143], v[152:155], v[20:35]
	ds_read_b128 v[152:155], v192 offset:4704
	ds_read_b128 v[140:143], v192 offset:64
	v_mfma_f32_32x32x16_bf16 v[52:67], v[136:139], v[156:159], v[52:67]
	ds_read_b128 v[160:163], v191 offset:36960
	ds_read_b128 v[136:139], v191 offset:41536
	v_mfma_f32_32x32x16_bf16 v[20:35], v[144:147], v[156:159], v[20:35]
	ds_read_b128 v[156:159], v191 offset:36928
	ds_read_b128 v[144:147], v192 offset:96
	s_waitcnt lgkmcnt(1)
	v_mfma_f32_32x32x16_bf16 v[52:67], v[140:143], v[156:159], v[52:67]
	s_waitcnt vmcnt(11)
	ds_write_b16 v199, v128
	v_mfma_f32_32x32x16_bf16 v[36:51], v[140:143], v[136:139], v[36:51]
	ds_write_b16_d16_hi v199, v128 offset:144
	v_mfma_f32_32x32x16_bf16 v[20:35], v[132:135], v[156:159], v[20:35]
	ds_write_b16 v199, v129 offset:288
	v_mfma_f32_32x32x16_bf16 v[4:19], v[132:135], v[136:139], v[4:19]
	s_setprio 0
	ds_write_b16_d16_hi v199, v129 offset:432
	s_waitcnt lgkmcnt(4)
	v_mfma_f32_32x32x16_bf16 v[52:67], v[144:147], v[160:163], v[52:67]
	ds_write_b16 v199, v130 offset:576
	v_mfma_f32_32x32x16_bf16 v[36:51], v[144:147], v[164:167], v[36:51]
	ds_write_b16_d16_hi v199, v130 offset:720
	v_mfma_f32_32x32x16_bf16 v[20:35], v[152:155], v[160:163], v[20:35]
	ds_write_b16 v199, v131 offset:864
	v_mfma_f32_32x32x16_bf16 v[4:19], v[152:155], v[164:167], v[4:19]
	ds_write_b16_d16_hi v199, v131 offset:1008
	ds_write_b128 v198, v[104:107] offset:36864
	s_waitcnt vmcnt(10)
	ds_write_b16 v197, v120 offset:1152
	ds_write_b16_d16_hi v197, v120 offset:1296
	ds_write_b16 v197, v121 offset:1440
	ds_write_b16_d16_hi v197, v121 offset:1584
	ds_write_b16 v197, v122 offset:1728
	ds_write_b16_d16_hi v197, v122 offset:1872
	ds_write_b16 v197, v123 offset:2016
	ds_write_b16_d16_hi v197, v123 offset:2160
	ds_write_b128 v196, v[88:91] offset:36864
	s_waitcnt vmcnt(9)
	ds_write_b16 v195, v112 offset:2304
	ds_write_b16_d16_hi v195, v112 offset:2448
	ds_write_b16 v195, v113 offset:2592
	ds_write_b16_d16_hi v195, v113 offset:2736
	ds_write_b16 v195, v114 offset:2880
	ds_write_b16_d16_hi v195, v114 offset:3024
	ds_write_b16 v195, v115 offset:3168
	ds_write_b16_d16_hi v195, v115 offset:3312
	ds_write_b128 v194, v[80:83] offset:36864
	s_waitcnt vmcnt(8)
	ds_write_b16 v193, v96 offset:3456
	ds_write_b16_d16_hi v193, v96 offset:3600
	ds_write_b16 v193, v97 offset:3744
	ds_write_b16_d16_hi v193, v97 offset:3888
	ds_write_b16 v193, v98 offset:4032
	ds_write_b16_d16_hi v193, v98 offset:4176
	ds_write_b16 v193, v99 offset:4320
	ds_write_b16_d16_hi v193, v99 offset:4464
	ds_write_b128 v2, v[72:75] offset:36864
	s_waitcnt lgkmcnt(0)
	s_barrier
	s_setprio 1
	ds_read_b128 v[72:75], v201
	ds_read_b128 v[80:83], v201 offset:32
	ds_read_b128 v[88:91], v201 offset:4608
	ds_read_b128 v[96:99], v201 offset:4640
	ds_read_b128 v[104:107], v200 offset:36864
	ds_read_b128 v[112:115], v200 offset:36896
	ds_read_b128 v[120:123], v200 offset:41472
	ds_read_b128 v[128:131], v200 offset:41504
	s_waitcnt lgkmcnt(3)
	v_mfma_f32_32x32x16_bf16 v[52:67], v[72:75], v[104:107], v[52:67]
	s_waitcnt lgkmcnt(1)
	v_mfma_f32_32x32x16_bf16 v[36:51], v[72:75], v[120:123], v[36:51]
	v_mfma_f32_32x32x16_bf16 v[4:19], v[88:91], v[120:123], v[4:19]
	s_waitcnt lgkmcnt(0)
	v_mfma_f32_32x32x16_bf16 v[36:51], v[80:83], v[128:131], v[36:51]
	v_mfma_f32_32x32x16_bf16 v[4:19], v[96:99], v[128:131], v[4:19]
	ds_read_b128 v[128:131], v200 offset:41568
	ds_read_b128 v[72:75], v201 offset:4672
	v_mfma_f32_32x32x16_bf16 v[20:35], v[88:91], v[104:107], v[20:35]
	ds_read_b128 v[104:107], v201 offset:4704
	ds_read_b128 v[88:91], v201 offset:64
	v_mfma_f32_32x32x16_bf16 v[52:67], v[80:83], v[112:115], v[52:67]
	ds_read_b128 v[120:123], v200 offset:36960
	ds_read_b128 v[80:83], v200 offset:41536
	v_mfma_f32_32x32x16_bf16 v[20:35], v[96:99], v[112:115], v[20:35]
	ds_read_b128 v[112:115], v200 offset:36928
	ds_read_b128 v[96:99], v201 offset:96
	s_waitcnt lgkmcnt(1)
	v_mfma_f32_32x32x16_bf16 v[52:67], v[88:91], v[112:115], v[52:67]
	s_waitcnt vmcnt(3)
; template <class Epi, class ColV>
; DI void gemm_tile(const bf16_t* __restrict__ A, int lda, const bf16_t* __restrict__ Bt, int ldb, int K, int m0, int n0, unsigned char* smem, Epi epi, ColV colv, const bf16_t* __restrict__ HYT = nullptr) {
;     ...
;     auto step = [&](int kt, u32x4 (&ldset)[8], const u32x4 (&stset)[8]) {
;         const int buf = kt & 1;
;         if (kt + 2 < nk) gload(ldset, kt + 2);
;         const bf16_t* Ab = As + (buf * 128 + 64 * wr + li) * LS + 8 * lh;
;         const bf16_t* Bb = Bs + (buf * 128 + 64 * wc + li) * LS + 8 * lh;
;         bf16x8 fa[2][2], fb[2][2], ga[2][2], gb[2][2];
; #pragma unroll
;         for (int k2 = 0; k2 < 2; ++k2) { fa[k2][0] = ld8(Ab + 16 * k2); fa[k2][1] = ld8(Ab + 32 * LS + 16 * k2); fb[k2][0] = ld8(Bb + 16 * k2); fb[k2][1] = ld8(Bb + 32 * LS + 16 * k2); }
;         __builtin_amdgcn_sched_barrier(0);
; #pragma unroll
;         for (int k2 = 0; k2 < 2; ++k2) {
;             acc[0][0] = MFMA(fa[k2][0], fb[k2][0], acc[0][0]); acc[0][1] = MFMA(fa[k2][0], fb[k2][1], acc[0][1]);
;             acc[1][0] = MFMA(fa[k2][1], fb[k2][0], acc[1][0]); acc[1][1] = MFMA(fa[k2][1], fb[k2][1], acc[1][1]);
;         }
; #pragma unroll
;         for (int k2 = 0; k2 < 2; ++k2) { const int ks = 2 + k2; ga[k2][0] = ld8(Ab + 16 * ks); ga[k2][1] = ld8(Ab + 32 * LS + 16 * ks); gb[k2][0] = ld8(Bb + 16 * ks); gb[k2][1] = ld8(Bb + 32 * LS + 16 * ks); }
; #pragma unroll
;         for (int k2 = 0; k2 < 2; ++k2) {
;             acc[0][0] = MFMA(ga[k2][0], gb[k2][0], acc[0][0]); acc[0][1] = MFMA(ga[k2][0], gb[k2][1], acc[0][1]);
;             acc[1][0] = MFMA(ga[k2][1], gb[k2][0], acc[1][0]); acc[1][1] = MFMA(ga[k2][1], gb[k2][1], acc[1][1]);
;         }
;         if (kt + 1 < nk) sstore(stset, buf ^ 1, kt + 1);
; #pragma unroll
;         for (int i = 0; i < 8; ++i) { __builtin_amdgcn_sched_group_barrier(0x008, 1, 0); __builtin_amdgcn_sched_group_barrier(0x100, 1, 0); }
; #pragma unroll
;         for (int i = 0; i < 8; ++i) { __builtin_amdgcn_sched_group_barrier(0x008, 1, 0); __builtin_amdgcn_sched_group_barrier(0x200, 1, 0); }
;         __builtin_amdgcn_sched_barrier(0);
;         __syncthreads();
;     };
;     gload(R0, 0); gload(R1, 1);
;     sstore(R0, 0, 0); __syncthreads();
;     for (int kt = 0; kt < nk; kt += 2) {
;         step(kt, R0, R1);
;         if (kt + 1 < nk) step(kt + 1, R1, R0);
;     }
	ds_write_b16 v199, v124 offset:18432
	v_mfma_f32_32x32x16_bf16 v[36:51], v[88:91], v[80:83], v[36:51]
	ds_write_b16_d16_hi v199, v124 offset:18576
	v_mfma_f32_32x32x16_bf16 v[20:35], v[72:75], v[112:115], v[20:35]
	ds_write_b16 v199, v125 offset:18720
	v_mfma_f32_32x32x16_bf16 v[4:19], v[72:75], v[80:83], v[4:19]
	s_setprio 0
	ds_write_b16_d16_hi v199, v125 offset:18864
	s_waitcnt lgkmcnt(4)
	v_mfma_f32_32x32x16_bf16 v[52:67], v[96:99], v[120:123], v[52:67]
	ds_write_b16 v199, v126 offset:19008
	v_mfma_f32_32x32x16_bf16 v[36:51], v[96:99], v[128:131], v[36:51]
	ds_write_b16_d16_hi v199, v126 offset:19152
	v_mfma_f32_32x32x16_bf16 v[20:35], v[104:107], v[120:123], v[20:35]
	ds_write_b16 v199, v127 offset:19296
	v_mfma_f32_32x32x16_bf16 v[4:19], v[104:107], v[128:131], v[4:19]
	ds_write_b16_d16_hi v199, v127 offset:19440
	ds_write_b128 v198, v[100:103] offset:55296
	s_waitcnt vmcnt(2)
	ds_write_b16 v197, v116 offset:19584
	ds_write_b16_d16_hi v197, v116 offset:19728
	ds_write_b16 v197, v117 offset:19872
	ds_write_b16_d16_hi v197, v117 offset:20016
	ds_write_b16 v197, v118 offset:20160
	ds_write_b16_d16_hi v197, v118 offset:20304
	ds_write_b16 v197, v119 offset:20448
	ds_write_b16_d16_hi v197, v119 offset:20592
	ds_write_b128 v196, v[84:87] offset:55296
	s_waitcnt vmcnt(1)
	ds_write_b16 v195, v108 offset:20736
	ds_write_b16_d16_hi v195, v108 offset:20880
	ds_write_b16 v195, v109 offset:21024
	ds_write_b16_d16_hi v195, v109 offset:21168
	ds_write_b16 v195, v110 offset:21312
	ds_write_b16_d16_hi v195, v110 offset:21456
	ds_write_b16 v195, v111 offset:21600
	ds_write_b16_d16_hi v195, v111 offset:21744
	ds_write_b128 v194, v[76:79] offset:55296
	s_waitcnt vmcnt(0)
	ds_write_b16 v193, v92 offset:21888
	ds_write_b16_d16_hi v193, v92 offset:22032
	ds_write_b16 v193, v93 offset:22176
	ds_write_b16_d16_hi v193, v93 offset:22320
	ds_write_b16 v193, v94 offset:22464
	ds_write_b16_d16_hi v193, v94 offset:22608
	ds_write_b16 v193, v95 offset:22752
	ds_write_b16_d16_hi v193, v95 offset:22896
	ds_write_b128 v2, v[68:71] offset:55296
	s_waitcnt lgkmcnt(0)
	s_barrier
	s_setprio 1
	ds_read_b128 v[68:71], v192
	ds_read_b128 v[72:75], v192 offset:32
	ds_read_b128 v[76:79], v192 offset:4608
	ds_read_b128 v[80:83], v192 offset:4640
	ds_read_b128 v[84:87], v191 offset:36864
	ds_read_b128 v[88:91], v191 offset:36896
	ds_read_b128 v[92:95], v191 offset:41472
	ds_read_b128 v[96:99], v191 offset:41504
	s_waitcnt lgkmcnt(3)
	v_mfma_f32_32x32x16_bf16 v[52:67], v[68:71], v[84:87], v[52:67]
	s_waitcnt lgkmcnt(1)
	v_mfma_f32_32x32x16_bf16 v[36:51], v[68:71], v[92:95], v[36:51]
	v_mfma_f32_32x32x16_bf16 v[4:19], v[76:79], v[92:95], v[4:19]
	s_waitcnt lgkmcnt(0)
	v_mfma_f32_32x32x16_bf16 v[36:51], v[72:75], v[96:99], v[36:51]
	v_mfma_f32_32x32x16_bf16 v[4:19], v[80:83], v[96:99], v[4:19]
	ds_read_b128 v[96:99], v191 offset:41568
	ds_read_b128 v[68:71], v192 offset:4672
	v_mfma_f32_32x32x16_bf16 v[20:35], v[76:79], v[84:87], v[20:35]
	ds_read_b128 v[84:87], v192 offset:4704
	ds_read_b128 v[76:79], v192 offset:64
	v_mfma_f32_32x32x16_bf16 v[52:67], v[72:75], v[88:91], v[52:67]
	ds_read_b128 v[92:95], v191 offset:36960
	ds_read_b128 v[72:75], v191 offset:41536
	v_mfma_f32_32x32x16_bf16 v[20:35], v[80:83], v[88:91], v[20:35]
	ds_read_b128 v[88:91], v191 offset:36928
	ds_read_b128 v[80:83], v192 offset:96
	s_waitcnt lgkmcnt(1)
	v_mfma_f32_32x32x16_bf16 v[52:67], v[76:79], v[88:91], v[52:67]
	v_mfma_f32_32x32x16_bf16 v[36:51], v[76:79], v[72:75], v[36:51]
	v_mfma_f32_32x32x16_bf16 v[20:35], v[68:71], v[88:91], v[20:35]
	v_mfma_f32_32x32x16_bf16 v[4:19], v[68:71], v[72:75], v[4:19]
	s_setprio 0
	s_waitcnt lgkmcnt(0)
	v_mfma_f32_32x32x16_bf16 v[52:67], v[80:83], v[92:95], v[52:67]
	v_mfma_f32_32x32x16_bf16 v[36:51], v[80:83], v[96:99], v[36:51]
	v_mfma_f32_32x32x16_bf16 v[20:35], v[84:87], v[92:95], v[20:35]
	v_mfma_f32_32x32x16_bf16 v[4:19], v[84:87], v[96:99], v[4:19]
	s_min_i32 s13, s12, 0x4000
	s_ashr_i32 s13, s13, 12
	s_mulk_i32 s13, 0x1800
	v_bitop3_b32 v68, v151, 31, 64 bitop3:0xe0
	v_or_b32_e32 v0, s13, v68
	v_subrev_u32_e32 v0, s38, v0
	v_add_u32_e32 v2, s36, v0
	v_add_u32_e32 v0, 0x800, v2
	v_ashrrev_i32_e32 v1, 31, v0
	v_lshl_add_u64 v[0:1], v[0:1], 2, s[46:47]
	s_barrier
	s_setprio 1
	global_load_dword v108, v[0:1], off
	v_add_u32_e32 v0, 0x820, v2
	v_ashrrev_i32_e32 v1, 31, v0
	v_lshl_add_u64 v[0:1], v[0:1], 2, s[46:47]
	global_load_dword v2, v[0:1], off
	v_add_u32_e32 v0, s12, v190
	v_lshl_or_b32 v109, v148, 2, v0
	v_subrev_u32_e32 v0, s38, v68
	v_add_u32_e32 v0, s36, v0
	s_cmp_lt_i32 s12, 0x4000
	s_cselect_b32 s100, s15, s48
	s_cselect_b32 s101, s9, s49
	s_cselect_b32 s13, 0, 0x4000
	v_subrev_u32_e32 v109, s13, v109
	v_lshlrev_b32_e32 v109, 12, v109
	v_lshl_add_u32 v109, v0, 2, v109
	s_cselect_b32 s12, s24, s96
	s_cselect_b32 s13, s25, s97
	v_mov_b32_e32 v0, v109
	global_load_dword v69, v0, s[100:101]
	global_load_dword v70, v0, s[100:101] offset:128
	v_add_u32_e32 v0, 0x1000, v0
	global_load_dword v71, v0, s[100:101]
	global_load_dword v72, v0, s[100:101] offset:128
	v_add_u32_e32 v0, 0x1000, v0
	global_load_dword v73, v0, s[100:101]
	global_load_dword v74, v0, s[100:101] offset:128
	v_add_u32_e32 v0, 0x1000, v0
	global_load_dword v75, v0, s[100:101]
	global_load_dword v76, v0, s[100:101] offset:128
	v_add_u32_e32 v0, 0x5000, v0
	global_load_dword v77, v0, s[100:101]
	global_load_dword v78, v0, s[100:101] offset:128
	v_add_u32_e32 v0, 0x1000, v0
	global_load_dword v79, v0, s[100:101]
	global_load_dword v80, v0, s[100:101] offset:128
	v_add_u32_e32 v0, 0x1000, v0
	global_load_dword v81, v0, s[100:101]
	global_load_dword v82, v0, s[100:101] offset:128
; DI int crow(int reg, int h) { return (reg & 3) + 8 * (reg >> 2) + 4 * h; }
; template <class Epi, class ColV>
; DI void gemm_tile(const bf16_t* __restrict__ A, int lda, const bf16_t* __restrict__ Bt, int ldb, int K, int m0, int n0, unsigned char* smem, Epi epi, ColV colv, const bf16_t* __restrict__ HYT = nullptr) {
;     ...
;     const float cv0 = colv(m0, n0 + 64 * wc + li), cv1 = colv(m0, n0 + 64 * wc + 32 + li);
; #pragma unroll
;     for (int mi = 0; mi < 2; ++mi)
; #pragma unroll
;         for (int ni = 0; ni < 2; ++ni)
; #pragma unroll
;             for (int reg = 0; reg < 16; ++reg)
;                 epi(m0 + 64 * wr + 32 * mi + crow(reg, lh), n0 + 64 * wc + 32 * ni + li, acc[mi][ni][reg], ni ? cv1 : cv0);
;     ...
;         auto epi = [&](int r, int c, float v, float ga) {
;             if (r < NL) { const size_t o = (size_t)r * 1024 + c; out[o] = (layer == 0 ? xin[o] : out[o]) + ga * v; }
;             else { const size_t o = (size_t)(r - NL) * 1024 + c; XC[o] = cin[o] + ga * v; } };
	v_add_u32_e32 v0, 0x1000, v0
	global_load_dword v83, v0, s[100:101]
	global_load_dword v84, v0, s[100:101] offset:128
	v_add_u32_e32 v0, 0x5000, v0
	global_load_dword v85, v0, s[100:101]
	global_load_dword v86, v0, s[100:101] offset:128
	v_add_u32_e32 v0, 0x1000, v0
	global_load_dword v87, v0, s[100:101]
	global_load_dword v88, v0, s[100:101] offset:128
	v_add_u32_e32 v0, 0x1000, v0
	global_load_dword v89, v0, s[100:101]
	global_load_dword v90, v0, s[100:101] offset:128
	v_add_u32_e32 v0, 0x1000, v0
	global_load_dword v91, v0, s[100:101]
	global_load_dword v92, v0, s[100:101] offset:128
	v_add_u32_e32 v0, 0x5000, v0
	global_load_dword v93, v0, s[100:101]
	global_load_dword v94, v0, s[100:101] offset:128
	v_add_u32_e32 v0, 0x1000, v0
	global_load_dword v95, v0, s[100:101]
	global_load_dword v96, v0, s[100:101] offset:128
	v_add_u32_e32 v0, 0x1000, v0
	global_load_dword v97, v0, s[100:101]
	global_load_dword v98, v0, s[100:101] offset:128
	v_add_u32_e32 v0, 0x1000, v0
	global_load_dword v99, v0, s[100:101]
	global_load_dword v100, v0, s[100:101] offset:128
	v_add_u32_e32 v0, 0x20000, v109
	global_load_dword v101, v0, s[100:101]
	global_load_dword v102, v0, s[100:101] offset:128
	v_add_u32_e32 v0, 0x1000, v0
	global_load_dword v103, v0, s[100:101]
	global_load_dword v104, v0, s[100:101] offset:128
	v_add_u32_e32 v0, 0x1000, v0
	global_load_dword v105, v0, s[100:101]
	global_load_dword v106, v0, s[100:101] offset:128
	v_add_u32_e32 v0, 0x1000, v0
	global_load_dword v107, v0, s[100:101]
	global_load_dword v110, v0, s[100:101] offset:128
	v_add_u32_e32 v0, 0x5000, v0
	global_load_dword v111, v0, s[100:101]
	global_load_dword v112, v0, s[100:101] offset:128
	v_add_u32_e32 v0, 0x1000, v0
	global_load_dword v113, v0, s[100:101]
	global_load_dword v114, v0, s[100:101] offset:128
	v_add_u32_e32 v0, 0x1000, v0
	global_load_dword v115, v0, s[100:101]
	global_load_dword v116, v0, s[100:101] offset:128
	v_add_u32_e32 v0, 0x1000, v0
	global_load_dword v117, v0, s[100:101]
	global_load_dword v118, v0, s[100:101] offset:128
	v_add_u32_e32 v0, 0x5000, v0
	global_load_dword v119, v0, s[100:101]
	global_load_dword v120, v0, s[100:101] offset:128
	v_add_u32_e32 v0, 0x1000, v0
	global_load_dword v121, v0, s[100:101]
	global_load_dword v122, v0, s[100:101] offset:128
	v_add_u32_e32 v0, 0x1000, v0
	global_load_dword v123, v0, s[100:101]
	global_load_dword v124, v0, s[100:101] offset:128
	v_add_u32_e32 v0, 0x1000, v0
	global_load_dword v125, v0, s[100:101]
	global_load_dword v126, v0, s[100:101] offset:128
	v_add_u32_e32 v0, 0x5000, v0
	global_load_dword v127, v0, s[100:101]
	global_load_dword v128, v0, s[100:101] offset:128
	v_add_u32_e32 v0, 0x1000, v0
	global_load_dword v129, v0, s[100:101]
	global_load_dword v130, v0, s[100:101] offset:128
	v_add_u32_e32 v0, 0x1000, v0
	global_load_dword v131, v0, s[100:101]
	global_load_dword v132, v0, s[100:101] offset:128
	v_add_u32_e32 v0, 0x1000, v0
	global_load_dword v133, v0, s[100:101]
	global_load_dword v134, v0, s[100:101] offset:128
	s_waitcnt vmcnt(32)
; DI int crow(int reg, int h) { return (reg & 3) + 8 * (reg >> 2) + 4 * h; }
; #define XCD_TILE_LOOP(MT, NTN, m_, n_) for (int lt_ = (bid >> 3), m_ = 0, n_ = 0; (lt_ < ((MT) >> 3) * (NTN)) && ((m_ = (bid & 7) + 8 * (lt_ / (NTN))), (n_ = lt_ % (NTN)), true); lt_ += (G >> 3))
; template <class Epi, class ColV>
; DI void gemm_tile(const bf16_t* __restrict__ A, int lda, const bf16_t* __restrict__ Bt, int ldb, int K, int m0, int n0, unsigned char* smem, Epi epi, ColV colv, const bf16_t* __restrict__ HYT = nullptr) {
;     ...
;     const float cv0 = colv(m0, n0 + 64 * wc + li), cv1 = colv(m0, n0 + 64 * wc + 32 + li);
; #pragma unroll
;     for (int mi = 0; mi < 2; ++mi)
; #pragma unroll
;         for (int ni = 0; ni < 2; ++ni)
; #pragma unroll
;             for (int reg = 0; reg < 16; ++reg)
;                 epi(m0 + 64 * wr + 32 * mi + crow(reg, lh), n0 + 64 * wc + 32 * ni + li, acc[mi][ni][reg], ni ? cv1 : cv0);
;     ...
;         auto epi = [&](int r, int c, float v, float ga) {
;             if (r < NL) { const size_t o = (size_t)r * 1024 + c; out[o] = (layer == 0 ? xin[o] : out[o]) + ga * v; }
;             else { const size_t o = (size_t)(r - NL) * 1024 + c; XC[o] = cin[o] + ga * v; } };
;         XCD_TILE_LOOP((layer == 0 ? NT : NL) / 128, 8, tm, tn) gemm_tile((const bf16_t*)(p.ws + WS_MIX), 1024, (const bf16_t*)(p.ws + wbase(layer) + W_OUT), 1024, 1024, tm * 128, tn * 128, smem, epi, gate, (const bf16_t*)(p.ws + WS_HYOT));
	v_fmac_f32_e32 v69, v52, v108
	v_fmac_f32_e32 v70, v36, v2
	v_fmac_f32_e32 v71, v53, v108
	v_fmac_f32_e32 v72, v37, v2
	v_fmac_f32_e32 v73, v54, v108
	v_fmac_f32_e32 v74, v38, v2
	v_fmac_f32_e32 v75, v55, v108
	v_fmac_f32_e32 v76, v39, v2
	v_fmac_f32_e32 v77, v56, v108
	v_fmac_f32_e32 v78, v40, v2
	v_fmac_f32_e32 v79, v57, v108
	v_fmac_f32_e32 v80, v41, v2
	v_fmac_f32_e32 v81, v58, v108
	v_fmac_f32_e32 v82, v42, v2
	v_fmac_f32_e32 v83, v59, v108
	v_fmac_f32_e32 v84, v43, v2
	v_fmac_f32_e32 v85, v60, v108
	v_fmac_f32_e32 v86, v44, v2
	v_fmac_f32_e32 v87, v61, v108
	v_fmac_f32_e32 v88, v45, v2
	v_fmac_f32_e32 v89, v62, v108
	v_fmac_f32_e32 v90, v46, v2
	v_fmac_f32_e32 v91, v63, v108
	v_fmac_f32_e32 v92, v47, v2
	v_fmac_f32_e32 v93, v64, v108
	v_fmac_f32_e32 v94, v48, v2
	v_fmac_f32_e32 v95, v65, v108
	v_fmac_f32_e32 v96, v49, v2
	v_fmac_f32_e32 v97, v66, v108
	v_fmac_f32_e32 v98, v50, v2
	v_fmac_f32_e32 v99, v67, v108
	v_fmac_f32_e32 v100, v51, v2
	v_mov_b32_e32 v0, v109
	global_store_dword v0, v69, s[12:13]
	global_store_dword v0, v70, s[12:13] offset:128
	v_add_u32_e32 v0, 0x1000, v0
	global_store_dword v0, v71, s[12:13]
	global_store_dword v0, v72, s[12:13] offset:128
	v_add_u32_e32 v0, 0x1000, v0
	global_store_dword v0, v73, s[12:13]
	global_store_dword v0, v74, s[12:13] offset:128
	v_add_u32_e32 v0, 0x1000, v0
	global_store_dword v0, v75, s[12:13]
	global_store_dword v0, v76, s[12:13] offset:128
	v_add_u32_e32 v0, 0x5000, v0
	global_store_dword v0, v77, s[12:13]
	global_store_dword v0, v78, s[12:13] offset:128
	v_add_u32_e32 v0, 0x1000, v0
	global_store_dword v0, v79, s[12:13]
	global_store_dword v0, v80, s[12:13] offset:128
	v_add_u32_e32 v0, 0x1000, v0
	global_store_dword v0, v81, s[12:13]
	global_store_dword v0, v82, s[12:13] offset:128
	v_add_u32_e32 v0, 0x1000, v0
	global_store_dword v0, v83, s[12:13]
	global_store_dword v0, v84, s[12:13] offset:128
	v_add_u32_e32 v0, 0x5000, v0
	global_store_dword v0, v85, s[12:13]
	global_store_dword v0, v86, s[12:13] offset:128
	v_add_u32_e32 v0, 0x1000, v0
	global_store_dword v0, v87, s[12:13]
	global_store_dword v0, v88, s[12:13] offset:128
	v_add_u32_e32 v0, 0x1000, v0
	global_store_dword v0, v89, s[12:13]
	global_store_dword v0, v90, s[12:13] offset:128
	v_add_u32_e32 v0, 0x1000, v0
	global_store_dword v0, v91, s[12:13]
	global_store_dword v0, v92, s[12:13] offset:128
	v_add_u32_e32 v0, 0x5000, v0
	global_store_dword v0, v93, s[12:13]
	global_store_dword v0, v94, s[12:13] offset:128
	v_add_u32_e32 v0, 0x1000, v0
	global_store_dword v0, v95, s[12:13]
	global_store_dword v0, v96, s[12:13] offset:128
	v_add_u32_e32 v0, 0x1000, v0
	global_store_dword v0, v97, s[12:13]
	global_store_dword v0, v98, s[12:13] offset:128
	v_add_u32_e32 v0, 0x1000, v0
	global_store_dword v0, v99, s[12:13]
	global_store_dword v0, v100, s[12:13] offset:128
	s_waitcnt vmcnt(32)
	v_fmac_f32_e32 v101, v20, v108
	v_fmac_f32_e32 v102, v4, v2
	v_fmac_f32_e32 v103, v21, v108
	v_fmac_f32_e32 v104, v5, v2
	v_fmac_f32_e32 v105, v22, v108
	v_fmac_f32_e32 v106, v6, v2
	v_fmac_f32_e32 v107, v23, v108
	v_fmac_f32_e32 v110, v7, v2
	v_fmac_f32_e32 v111, v24, v108
	v_fmac_f32_e32 v112, v8, v2
	v_fmac_f32_e32 v113, v25, v108
	v_fmac_f32_e32 v114, v9, v2
	v_fmac_f32_e32 v115, v26, v108
	v_fmac_f32_e32 v116, v10, v2
	v_fmac_f32_e32 v117, v27, v108
	v_fmac_f32_e32 v118, v11, v2
	v_fmac_f32_e32 v119, v28, v108
	v_fmac_f32_e32 v120, v12, v2
	v_fmac_f32_e32 v121, v29, v108
	v_fmac_f32_e32 v122, v13, v2
	v_fmac_f32_e32 v123, v30, v108
	v_fmac_f32_e32 v124, v14, v2
	v_fmac_f32_e32 v125, v31, v108
	v_fmac_f32_e32 v126, v15, v2
	v_fmac_f32_e32 v127, v32, v108
	v_fmac_f32_e32 v128, v16, v2
	v_fmac_f32_e32 v129, v33, v108
	v_fmac_f32_e32 v130, v17, v2
	v_fmac_f32_e32 v131, v34, v108
	v_fmac_f32_e32 v132, v18, v2
	v_fmac_f32_e32 v133, v35, v108
	v_fmac_f32_e32 v134, v19, v2
	v_add_u32_e32 v0, 0x20000, v109
	global_store_dword v0, v101, s[12:13]
	global_store_dword v0, v102, s[12:13] offset:128
	v_add_u32_e32 v0, 0x1000, v0
	global_store_dword v0, v103, s[12:13]
	global_store_dword v0, v104, s[12:13] offset:128
	v_add_u32_e32 v0, 0x1000, v0
	global_store_dword v0, v105, s[12:13]
	global_store_dword v0, v106, s[12:13] offset:128
	v_add_u32_e32 v0, 0x1000, v0
	global_store_dword v0, v107, s[12:13]
	global_store_dword v0, v110, s[12:13] offset:128
	v_add_u32_e32 v0, 0x5000, v0
	global_store_dword v0, v111, s[12:13]
	global_store_dword v0, v112, s[12:13] offset:128
	v_add_u32_e32 v0, 0x1000, v0
	global_store_dword v0, v113, s[12:13]
	global_store_dword v0, v114, s[12:13] offset:128
	v_add_u32_e32 v0, 0x1000, v0
	global_store_dword v0, v115, s[12:13]
	global_store_dword v0, v116, s[12:13] offset:128
	v_add_u32_e32 v0, 0x1000, v0
	global_store_dword v0, v117, s[12:13]
	global_store_dword v0, v118, s[12:13] offset:128
	v_add_u32_e32 v0, 0x5000, v0
	global_store_dword v0, v119, s[12:13]
	global_store_dword v0, v120, s[12:13] offset:128
	v_add_u32_e32 v0, 0x1000, v0
	global_store_dword v0, v121, s[12:13]
	global_store_dword v0, v122, s[12:13] offset:128
	v_add_u32_e32 v0, 0x1000, v0
	global_store_dword v0, v123, s[12:13]
	global_store_dword v0, v124, s[12:13] offset:128
	v_add_u32_e32 v0, 0x1000, v0
	global_store_dword v0, v125, s[12:13]
	global_store_dword v0, v126, s[12:13] offset:128
	v_add_u32_e32 v0, 0x5000, v0
	global_store_dword v0, v127, s[12:13]
	global_store_dword v0, v128, s[12:13] offset:128
	v_add_u32_e32 v0, 0x1000, v0
	global_store_dword v0, v129, s[12:13]
	global_store_dword v0, v130, s[12:13] offset:128
	v_add_u32_e32 v0, 0x1000, v0
	global_store_dword v0, v131, s[12:13]
	global_store_dword v0, v132, s[12:13] offset:128
	v_add_u32_e32 v0, 0x1000, v0
	global_store_dword v0, v133, s[12:13]
	global_store_dword v0, v134, s[12:13] offset:128
	s_add_i32 s37, s37, s18
	s_add_i32 s36, s36, s19
	s_cmp_lt_i32 s37, s8
	s_cbranch_scc1 .LBB0_79
	s_setprio 0
